# rwc scanner: kk vector fetched one step further ahead (one LDS wait per step instead of two), y partials written two steps at a time (ds_write2st64_b32)
# speedup vs baseline: 1.0106x; 1.0067x over previous
; #define LAS __attribute__((address_space(3)))
; __device__ __forceinline__ void phase_rwc(const int wvs, const Params& p, LAS unsigned char* lds, int layer, int wg0) {
;     ...
;       for (int t = 0; t < 32; ++t) {
;         const int tn = t + 2;
;         const f32x4 nw4 = *(const LAS f32x4*)(Wv + tn * 64), nkk4 = *(const LAS f32x4*)(Wv + 2048 + tn * 64), nb4 = *(const LAS f32x4*)(Wv + 4096 + tn * 64), nkd4 = *(const LAS f32x4*)(Wv + 6144 + tn * 64), nr4 = *(const LAS f32x4*)(Wv + 8192 + tn * 64);
;         const float nvv = Vv[tn * 16];
;         const f32x4 pa = S * kk4;
;         const f32x4 t1 = S * w4 + vv * kd4;
;         float sa = (pa[0] + pa[2]) + (pa[1] + pa[3]);
;         sa = row16_sum(sa);
;         S = t1 + sa * b4;
;         const f32x4 py = S * r4;
;         ypw[t * 256] = (py[0] + py[2]) + (py[1] + py[3]);
;         w4 = xw4; kk4 = xkk4; b4 = xb4; kd4 = xkd4; r4 = xr4; vv = xvv;
;         xw4 = nw4; xkk4 = nkk4; xb4 = nb4; xkd4 = nkd4; xr4 = nr4; xvv = nvv;
;       }
.Lrwc_scan:
	ds_read_b128 v[20:23], v80 offset:8192
	ds_read_b128 v[24:27], v80 offset:24576
	ds_read_b128 v[12:15], v81 offset:0
	ds_read_b128 v[28:31], v80 offset:0
	ds_read_b128 v[32:35], v80 offset:16384
	ds_read_b128 v[36:39], v80 offset:32768
	ds_read_b128 v[40:43], v80 offset:8448
	ds_read_b128 v[44:47], v80 offset:24832
	ds_read_b128 v[48:51], v80 offset:256
	ds_read_b128 v[52:55], v80 offset:16640
	ds_read_b128 v[56:59], v80 offset:33024
	ds_read_b128 v[60:63], v80 offset:8704
	s_waitcnt lgkmcnt(11)
	v_pk_mul_f32 v[6:7], v[22:23], v[4:5]
	v_pk_fma_f32 v[6:7], v[20:21], v[2:3], v[6:7]
	s_waitcnt lgkmcnt(6)
	v_add_f32_e32 v0, v6, v7
	v_pk_mul_f32 v[10:11], v[26:27], v[12:13] op_sel_hi:[1,0]
	v_pk_mul_f32 v[8:9], v[24:25], v[12:13] op_sel_hi:[1,0]
	v_add_f32_dpp v0, v0, v0 quad_perm:[1,0,3,2] row_mask:0xf bank_mask:0xf bound_ctrl:1
	v_pk_fma_f32 v[10:11], v[30:31], v[4:5], v[10:11]
	v_pk_fma_f32 v[8:9], v[28:29], v[2:3], v[8:9]
	v_add_f32_dpp v0, v0, v0 quad_perm:[2,3,0,1] row_mask:0xf bank_mask:0xf bound_ctrl:1
	ds_read_b128 v[64:67], v80 offset:25088
	ds_read_b128 v[68:71], v80 offset:512
	ds_read_b128 v[72:75], v80 offset:16896
	ds_read_b128 v[76:79], v80 offset:33280
	ds_read_b128 v[20:23], v80 offset:8960
	v_add_f32_dpp v0, v0, v0 row_half_mirror row_mask:0xf bank_mask:0xf bound_ctrl:1
	s_nop 1
	v_add_f32_dpp v0, v0, v0 row_mirror row_mask:0xf bank_mask:0xf bound_ctrl:1
	v_pk_fma_f32 v[4:5], v[34:35], v[0:1], v[10:11] op_sel_hi:[1,0,1]
	s_waitcnt lgkmcnt(10)
	v_pk_mul_f32 v[6:7], v[42:43], v[4:5]
	v_pk_fma_f32 v[2:3], v[32:33], v[0:1], v[8:9] op_sel_hi:[1,0,1]
	v_pk_fma_f32 v[6:7], v[40:41], v[2:3], v[6:7]
	s_waitcnt lgkmcnt(5)
	v_add_f32_e32 v0, v6, v7
	v_pk_mul_f32 v[6:7], v[38:39], v[4:5]
	v_pk_fma_f32 v[6:7], v[36:37], v[2:3], v[6:7]
	v_add_f32_dpp v0, v0, v0 quad_perm:[1,0,3,2] row_mask:0xf bank_mask:0xf bound_ctrl:1
	v_pk_mul_f32 v[10:11], v[46:47], v[12:13] op_sel:[0,1] op_sel_hi:[1,1]
	v_pk_mul_f32 v[8:9], v[44:45], v[12:13] op_sel:[0,1] op_sel_hi:[1,1]
	v_add_f32_dpp v0, v0, v0 quad_perm:[2,3,0,1] row_mask:0xf bank_mask:0xf bound_ctrl:1
	ds_read_b128 v[24:27], v80 offset:25344
	ds_read_b128 v[28:31], v80 offset:768
	ds_read_b128 v[32:35], v80 offset:17152
	ds_read_b128 v[36:39], v80 offset:33536
	ds_read_b128 v[40:43], v80 offset:9216
	ds_read_b128 v[16:19], v81 offset:16
	v_add_f32_e32 v86, v6, v7
	v_add_f32_dpp v0, v0, v0 row_half_mirror row_mask:0xf bank_mask:0xf bound_ctrl:1
	v_pk_fma_f32 v[10:11], v[50:51], v[4:5], v[10:11]
	v_pk_fma_f32 v[8:9], v[48:49], v[2:3], v[8:9]
	v_add_f32_dpp v0, v0, v0 row_mirror row_mask:0xf bank_mask:0xf bound_ctrl:1
	v_pk_fma_f32 v[4:5], v[54:55], v[0:1], v[10:11] op_sel_hi:[1,0,1]
	v_pk_mul_f32 v[6:7], v[62:63], v[4:5]
	v_pk_fma_f32 v[2:3], v[52:53], v[0:1], v[8:9] op_sel_hi:[1,0,1]
	v_pk_fma_f32 v[6:7], v[60:61], v[2:3], v[6:7]
	s_waitcnt lgkmcnt(6)
	v_add_f32_e32 v0, v6, v7
	v_pk_mul_f32 v[6:7], v[58:59], v[4:5]
	v_pk_fma_f32 v[6:7], v[56:57], v[2:3], v[6:7]
	v_add_f32_dpp v0, v0, v0 quad_perm:[1,0,3,2] row_mask:0xf bank_mask:0xf bound_ctrl:1
	v_pk_mul_f32 v[10:11], v[66:67], v[14:15] op_sel_hi:[1,0]
	v_pk_mul_f32 v[8:9], v[64:65], v[14:15] op_sel_hi:[1,0]
	v_add_f32_dpp v0, v0, v0 quad_perm:[2,3,0,1] row_mask:0xf bank_mask:0xf bound_ctrl:1
	ds_read_b128 v[44:47], v80 offset:25600
	ds_read_b128 v[48:51], v80 offset:1024
	ds_read_b128 v[52:55], v80 offset:17408
	ds_read_b128 v[56:59], v80 offset:33792
	ds_read_b128 v[60:63], v80 offset:9472
	v_add_f32_e32 v87, v6, v7
	ds_write2st64_b32 v82, v86, v87 offset0:0 offset1:4
	v_add_f32_dpp v0, v0, v0 row_half_mirror row_mask:0xf bank_mask:0xf bound_ctrl:1
	v_pk_fma_f32 v[10:11], v[70:71], v[4:5], v[10:11]
	v_pk_fma_f32 v[8:9], v[68:69], v[2:3], v[8:9]
	v_add_f32_dpp v0, v0, v0 row_mirror row_mask:0xf bank_mask:0xf bound_ctrl:1
	v_pk_fma_f32 v[4:5], v[74:75], v[0:1], v[10:11] op_sel_hi:[1,0,1]
	v_pk_mul_f32 v[6:7], v[22:23], v[4:5]
	v_pk_fma_f32 v[2:3], v[72:73], v[0:1], v[8:9] op_sel_hi:[1,0,1]
	v_pk_fma_f32 v[6:7], v[20:21], v[2:3], v[6:7]
	s_waitcnt lgkmcnt(7)
	v_add_f32_e32 v0, v6, v7
	v_pk_mul_f32 v[6:7], v[78:79], v[4:5]
	v_pk_fma_f32 v[6:7], v[76:77], v[2:3], v[6:7]
	v_add_f32_dpp v0, v0, v0 quad_perm:[1,0,3,2] row_mask:0xf bank_mask:0xf bound_ctrl:1
	v_pk_mul_f32 v[10:11], v[26:27], v[14:15] op_sel:[0,1] op_sel_hi:[1,1]
	v_pk_mul_f32 v[8:9], v[24:25], v[14:15] op_sel:[0,1] op_sel_hi:[1,1]
	v_add_f32_dpp v0, v0, v0 quad_perm:[2,3,0,1] row_mask:0xf bank_mask:0xf bound_ctrl:1
	ds_read_b128 v[64:67], v80 offset:25856
	ds_read_b128 v[68:71], v80 offset:1280
	ds_read_b128 v[72:75], v80 offset:17664
	ds_read_b128 v[76:79], v80 offset:34048
	ds_read_b128 v[20:23], v80 offset:9728
	v_add_f32_e32 v86, v6, v7
	v_add_f32_dpp v0, v0, v0 row_half_mirror row_mask:0xf bank_mask:0xf bound_ctrl:1
	v_pk_fma_f32 v[10:11], v[30:31], v[4:5], v[10:11]
	v_pk_fma_f32 v[8:9], v[28:29], v[2:3], v[8:9]
	v_add_f32_dpp v0, v0, v0 row_mirror row_mask:0xf bank_mask:0xf bound_ctrl:1
	v_pk_fma_f32 v[4:5], v[34:35], v[0:1], v[10:11] op_sel_hi:[1,0,1]
	v_pk_mul_f32 v[6:7], v[42:43], v[4:5]
	v_pk_fma_f32 v[2:3], v[32:33], v[0:1], v[8:9] op_sel_hi:[1,0,1]
	v_pk_fma_f32 v[6:7], v[40:41], v[2:3], v[6:7]
	s_waitcnt lgkmcnt(6)
; #define LAS __attribute__((address_space(3)))
; __device__ __forceinline__ void phase_rwc(const int wvs, const Params& p, LAS unsigned char* lds, int layer, int wg0) {
;     ...
;       for (int t = 0; t < 32; ++t) {
;         const int tn = t + 2;
;         const f32x4 nw4 = *(const LAS f32x4*)(Wv + tn * 64), nkk4 = *(const LAS f32x4*)(Wv + 2048 + tn * 64), nb4 = *(const LAS f32x4*)(Wv + 4096 + tn * 64), nkd4 = *(const LAS f32x4*)(Wv + 6144 + tn * 64), nr4 = *(const LAS f32x4*)(Wv + 8192 + tn * 64);
;         const float nvv = Vv[tn * 16];
;         const f32x4 pa = S * kk4;
;         const f32x4 t1 = S * w4 + vv * kd4;
;         float sa = (pa[0] + pa[2]) + (pa[1] + pa[3]);
;         sa = row16_sum(sa);
;         S = t1 + sa * b4;
;         const f32x4 py = S * r4;
;         ypw[t * 256] = (py[0] + py[2]) + (py[1] + py[3]);
;         w4 = xw4; kk4 = xkk4; b4 = xb4; kd4 = xkd4; r4 = xr4; vv = xvv;
;         xw4 = nw4; xkk4 = nkk4; xb4 = nb4; xkd4 = nkd4; xr4 = nr4; xvv = nvv;
;       }
	v_add_f32_e32 v0, v6, v7
	v_pk_mul_f32 v[6:7], v[38:39], v[4:5]
	v_pk_fma_f32 v[6:7], v[36:37], v[2:3], v[6:7]
	v_add_f32_dpp v0, v0, v0 quad_perm:[1,0,3,2] row_mask:0xf bank_mask:0xf bound_ctrl:1
	v_pk_mul_f32 v[10:11], v[46:47], v[16:17] op_sel_hi:[1,0]
	v_pk_mul_f32 v[8:9], v[44:45], v[16:17] op_sel_hi:[1,0]
	v_add_f32_dpp v0, v0, v0 quad_perm:[2,3,0,1] row_mask:0xf bank_mask:0xf bound_ctrl:1
	ds_read_b128 v[24:27], v80 offset:26112
	ds_read_b128 v[28:31], v80 offset:1536
	ds_read_b128 v[32:35], v80 offset:17920
	ds_read_b128 v[36:39], v80 offset:34304
	ds_read_b128 v[40:43], v80 offset:9984
	v_add_f32_e32 v87, v6, v7
	ds_write2st64_b32 v82, v86, v87 offset0:8 offset1:12
	v_add_f32_dpp v0, v0, v0 row_half_mirror row_mask:0xf bank_mask:0xf bound_ctrl:1
	v_pk_fma_f32 v[10:11], v[50:51], v[4:5], v[10:11]
	v_pk_fma_f32 v[8:9], v[48:49], v[2:3], v[8:9]
	v_add_f32_dpp v0, v0, v0 row_mirror row_mask:0xf bank_mask:0xf bound_ctrl:1
	v_pk_fma_f32 v[4:5], v[54:55], v[0:1], v[10:11] op_sel_hi:[1,0,1]
	v_pk_mul_f32 v[6:7], v[62:63], v[4:5]
	v_pk_fma_f32 v[2:3], v[52:53], v[0:1], v[8:9] op_sel_hi:[1,0,1]
	v_pk_fma_f32 v[6:7], v[60:61], v[2:3], v[6:7]
	s_waitcnt lgkmcnt(6)
	v_add_f32_e32 v0, v6, v7
	v_pk_mul_f32 v[6:7], v[58:59], v[4:5]
	v_pk_fma_f32 v[6:7], v[56:57], v[2:3], v[6:7]
	v_add_f32_dpp v0, v0, v0 quad_perm:[1,0,3,2] row_mask:0xf bank_mask:0xf bound_ctrl:1
	v_pk_mul_f32 v[10:11], v[66:67], v[16:17] op_sel:[0,1] op_sel_hi:[1,1]
	v_pk_mul_f32 v[8:9], v[64:65], v[16:17] op_sel:[0,1] op_sel_hi:[1,1]
	v_add_f32_dpp v0, v0, v0 quad_perm:[2,3,0,1] row_mask:0xf bank_mask:0xf bound_ctrl:1
	ds_read_b128 v[44:47], v80 offset:26368
	ds_read_b128 v[48:51], v80 offset:1792
	ds_read_b128 v[52:55], v80 offset:18176
	ds_read_b128 v[56:59], v80 offset:34560
	ds_read_b128 v[60:63], v80 offset:10240
	ds_read_b128 v[12:15], v81 offset:32
	v_add_f32_e32 v86, v6, v7
	v_add_f32_dpp v0, v0, v0 row_half_mirror row_mask:0xf bank_mask:0xf bound_ctrl:1
	v_pk_fma_f32 v[10:11], v[70:71], v[4:5], v[10:11]
	v_pk_fma_f32 v[8:9], v[68:69], v[2:3], v[8:9]
	v_add_f32_dpp v0, v0, v0 row_mirror row_mask:0xf bank_mask:0xf bound_ctrl:1
	v_pk_fma_f32 v[4:5], v[74:75], v[0:1], v[10:11] op_sel_hi:[1,0,1]
	v_pk_mul_f32 v[6:7], v[22:23], v[4:5]
	v_pk_fma_f32 v[2:3], v[72:73], v[0:1], v[8:9] op_sel_hi:[1,0,1]
	v_pk_fma_f32 v[6:7], v[20:21], v[2:3], v[6:7]
	s_waitcnt lgkmcnt(7)
	v_add_f32_e32 v0, v6, v7
	v_pk_mul_f32 v[6:7], v[78:79], v[4:5]
	v_pk_fma_f32 v[6:7], v[76:77], v[2:3], v[6:7]
	v_add_f32_dpp v0, v0, v0 quad_perm:[1,0,3,2] row_mask:0xf bank_mask:0xf bound_ctrl:1
	v_pk_mul_f32 v[10:11], v[26:27], v[18:19] op_sel_hi:[1,0]
	v_pk_mul_f32 v[8:9], v[24:25], v[18:19] op_sel_hi:[1,0]
	v_add_f32_dpp v0, v0, v0 quad_perm:[2,3,0,1] row_mask:0xf bank_mask:0xf bound_ctrl:1
	ds_read_b128 v[64:67], v80 offset:26624
	ds_read_b128 v[68:71], v80 offset:2048
	ds_read_b128 v[72:75], v80 offset:18432
	ds_read_b128 v[76:79], v80 offset:34816
	ds_read_b128 v[20:23], v80 offset:10496
	v_add_f32_e32 v87, v6, v7
	ds_write2st64_b32 v82, v86, v87 offset0:16 offset1:20
	v_add_f32_dpp v0, v0, v0 row_half_mirror row_mask:0xf bank_mask:0xf bound_ctrl:1
	v_pk_fma_f32 v[10:11], v[30:31], v[4:5], v[10:11]
	v_pk_fma_f32 v[8:9], v[28:29], v[2:3], v[8:9]
	v_add_f32_dpp v0, v0, v0 row_mirror row_mask:0xf bank_mask:0xf bound_ctrl:1
	v_pk_fma_f32 v[4:5], v[34:35], v[0:1], v[10:11] op_sel_hi:[1,0,1]
	v_pk_mul_f32 v[6:7], v[42:43], v[4:5]
	v_pk_fma_f32 v[2:3], v[32:33], v[0:1], v[8:9] op_sel_hi:[1,0,1]
	v_pk_fma_f32 v[6:7], v[40:41], v[2:3], v[6:7]
	s_waitcnt lgkmcnt(7)
	v_add_f32_e32 v0, v6, v7
	v_pk_mul_f32 v[6:7], v[38:39], v[4:5]
	v_pk_fma_f32 v[6:7], v[36:37], v[2:3], v[6:7]
	v_add_f32_dpp v0, v0, v0 quad_perm:[1,0,3,2] row_mask:0xf bank_mask:0xf bound_ctrl:1
	v_pk_mul_f32 v[10:11], v[46:47], v[18:19] op_sel:[0,1] op_sel_hi:[1,1]
	v_pk_mul_f32 v[8:9], v[44:45], v[18:19] op_sel:[0,1] op_sel_hi:[1,1]
	v_add_f32_dpp v0, v0, v0 quad_perm:[2,3,0,1] row_mask:0xf bank_mask:0xf bound_ctrl:1
	ds_read_b128 v[24:27], v80 offset:26880
	ds_read_b128 v[28:31], v80 offset:2304
	ds_read_b128 v[32:35], v80 offset:18688
	ds_read_b128 v[36:39], v80 offset:35072
	ds_read_b128 v[40:43], v80 offset:10752
	v_add_f32_e32 v86, v6, v7
	v_add_f32_dpp v0, v0, v0 row_half_mirror row_mask:0xf bank_mask:0xf bound_ctrl:1
	v_pk_fma_f32 v[10:11], v[50:51], v[4:5], v[10:11]
	v_pk_fma_f32 v[8:9], v[48:49], v[2:3], v[8:9]
	v_add_f32_dpp v0, v0, v0 row_mirror row_mask:0xf bank_mask:0xf bound_ctrl:1
	v_pk_fma_f32 v[4:5], v[54:55], v[0:1], v[10:11] op_sel_hi:[1,0,1]
	v_pk_mul_f32 v[6:7], v[62:63], v[4:5]
	v_pk_fma_f32 v[2:3], v[52:53], v[0:1], v[8:9] op_sel_hi:[1,0,1]
	v_pk_fma_f32 v[6:7], v[60:61], v[2:3], v[6:7]
	s_waitcnt lgkmcnt(6)
	v_add_f32_e32 v0, v6, v7
	v_pk_mul_f32 v[6:7], v[58:59], v[4:5]
	v_pk_fma_f32 v[6:7], v[56:57], v[2:3], v[6:7]
	v_add_f32_dpp v0, v0, v0 quad_perm:[1,0,3,2] row_mask:0xf bank_mask:0xf bound_ctrl:1
	v_pk_mul_f32 v[10:11], v[66:67], v[12:13] op_sel_hi:[1,0]
	v_pk_mul_f32 v[8:9], v[64:65], v[12:13] op_sel_hi:[1,0]
	v_add_f32_dpp v0, v0, v0 quad_perm:[2,3,0,1] row_mask:0xf bank_mask:0xf bound_ctrl:1
	ds_read_b128 v[44:47], v80 offset:27136
	ds_read_b128 v[48:51], v80 offset:2560
	ds_read_b128 v[52:55], v80 offset:18944
	ds_read_b128 v[56:59], v80 offset:35328
	ds_read_b128 v[60:63], v80 offset:11008
	v_add_f32_e32 v87, v6, v7
	ds_write2st64_b32 v82, v86, v87 offset0:24 offset1:28
	v_add_f32_dpp v0, v0, v0 row_half_mirror row_mask:0xf bank_mask:0xf bound_ctrl:1
	v_pk_fma_f32 v[10:11], v[70:71], v[4:5], v[10:11]
	v_pk_fma_f32 v[8:9], v[68:69], v[2:3], v[8:9]
	v_add_f32_dpp v0, v0, v0 row_mirror row_mask:0xf bank_mask:0xf bound_ctrl:1
	v_pk_fma_f32 v[4:5], v[74:75], v[0:1], v[10:11] op_sel_hi:[1,0,1]
	v_pk_mul_f32 v[6:7], v[22:23], v[4:5]
	v_pk_fma_f32 v[2:3], v[72:73], v[0:1], v[8:9] op_sel_hi:[1,0,1]
	v_pk_fma_f32 v[6:7], v[20:21], v[2:3], v[6:7]
	s_waitcnt lgkmcnt(6)
; #define LAS __attribute__((address_space(3)))
; __device__ __forceinline__ void phase_rwc(const int wvs, const Params& p, LAS unsigned char* lds, int layer, int wg0) {
;     ...
;       for (int t = 0; t < 32; ++t) {
;         const int tn = t + 2;
;         const f32x4 nw4 = *(const LAS f32x4*)(Wv + tn * 64), nkk4 = *(const LAS f32x4*)(Wv + 2048 + tn * 64), nb4 = *(const LAS f32x4*)(Wv + 4096 + tn * 64), nkd4 = *(const LAS f32x4*)(Wv + 6144 + tn * 64), nr4 = *(const LAS f32x4*)(Wv + 8192 + tn * 64);
;         const float nvv = Vv[tn * 16];
;         const f32x4 pa = S * kk4;
;         const f32x4 t1 = S * w4 + vv * kd4;
;         float sa = (pa[0] + pa[2]) + (pa[1] + pa[3]);
;         sa = row16_sum(sa);
;         S = t1 + sa * b4;
;         const f32x4 py = S * r4;
;         ypw[t * 256] = (py[0] + py[2]) + (py[1] + py[3]);
;         w4 = xw4; kk4 = xkk4; b4 = xb4; kd4 = xkd4; r4 = xr4; vv = xvv;
;         xw4 = nw4; xkk4 = nkk4; xb4 = nb4; xkd4 = nkd4; xr4 = nr4; xvv = nvv;
;       }
	v_add_f32_e32 v0, v6, v7
	v_pk_mul_f32 v[6:7], v[78:79], v[4:5]
	v_pk_fma_f32 v[6:7], v[76:77], v[2:3], v[6:7]
	v_add_f32_dpp v0, v0, v0 quad_perm:[1,0,3,2] row_mask:0xf bank_mask:0xf bound_ctrl:1
	v_pk_mul_f32 v[10:11], v[26:27], v[12:13] op_sel:[0,1] op_sel_hi:[1,1]
	v_pk_mul_f32 v[8:9], v[24:25], v[12:13] op_sel:[0,1] op_sel_hi:[1,1]
	v_add_f32_dpp v0, v0, v0 quad_perm:[2,3,0,1] row_mask:0xf bank_mask:0xf bound_ctrl:1
	ds_read_b128 v[64:67], v80 offset:27392
	ds_read_b128 v[68:71], v80 offset:2816
	ds_read_b128 v[72:75], v80 offset:19200
	ds_read_b128 v[76:79], v80 offset:35584
	ds_read_b128 v[20:23], v80 offset:11264
	ds_read_b128 v[16:19], v81 offset:48
	v_add_f32_e32 v86, v6, v7
	v_add_f32_dpp v0, v0, v0 row_half_mirror row_mask:0xf bank_mask:0xf bound_ctrl:1
	v_pk_fma_f32 v[10:11], v[30:31], v[4:5], v[10:11]
	v_pk_fma_f32 v[8:9], v[28:29], v[2:3], v[8:9]
	v_add_f32_dpp v0, v0, v0 row_mirror row_mask:0xf bank_mask:0xf bound_ctrl:1
	v_pk_fma_f32 v[4:5], v[34:35], v[0:1], v[10:11] op_sel_hi:[1,0,1]
	v_pk_mul_f32 v[6:7], v[42:43], v[4:5]
	v_pk_fma_f32 v[2:3], v[32:33], v[0:1], v[8:9] op_sel_hi:[1,0,1]
	v_pk_fma_f32 v[6:7], v[40:41], v[2:3], v[6:7]
	s_waitcnt lgkmcnt(7)
	v_add_f32_e32 v0, v6, v7
	v_pk_mul_f32 v[6:7], v[38:39], v[4:5]
	v_pk_fma_f32 v[6:7], v[36:37], v[2:3], v[6:7]
	v_add_f32_dpp v0, v0, v0 quad_perm:[1,0,3,2] row_mask:0xf bank_mask:0xf bound_ctrl:1
	v_pk_mul_f32 v[10:11], v[46:47], v[14:15] op_sel_hi:[1,0]
	v_pk_mul_f32 v[8:9], v[44:45], v[14:15] op_sel_hi:[1,0]
	v_add_f32_dpp v0, v0, v0 quad_perm:[2,3,0,1] row_mask:0xf bank_mask:0xf bound_ctrl:1
	ds_read_b128 v[24:27], v80 offset:27648
	ds_read_b128 v[28:31], v80 offset:3072
	ds_read_b128 v[32:35], v80 offset:19456
	ds_read_b128 v[36:39], v80 offset:35840
	ds_read_b128 v[40:43], v80 offset:11520
	v_add_f32_e32 v87, v6, v7
	ds_write2st64_b32 v82, v86, v87 offset0:32 offset1:36
	v_add_f32_dpp v0, v0, v0 row_half_mirror row_mask:0xf bank_mask:0xf bound_ctrl:1
	v_pk_fma_f32 v[10:11], v[50:51], v[4:5], v[10:11]
	v_pk_fma_f32 v[8:9], v[48:49], v[2:3], v[8:9]
	v_add_f32_dpp v0, v0, v0 row_mirror row_mask:0xf bank_mask:0xf bound_ctrl:1
	v_pk_fma_f32 v[4:5], v[54:55], v[0:1], v[10:11] op_sel_hi:[1,0,1]
	v_pk_mul_f32 v[6:7], v[62:63], v[4:5]
	v_pk_fma_f32 v[2:3], v[52:53], v[0:1], v[8:9] op_sel_hi:[1,0,1]
	v_pk_fma_f32 v[6:7], v[60:61], v[2:3], v[6:7]
	s_waitcnt lgkmcnt(7)
	v_add_f32_e32 v0, v6, v7
	v_pk_mul_f32 v[6:7], v[58:59], v[4:5]
	v_pk_fma_f32 v[6:7], v[56:57], v[2:3], v[6:7]
	v_add_f32_dpp v0, v0, v0 quad_perm:[1,0,3,2] row_mask:0xf bank_mask:0xf bound_ctrl:1
	v_pk_mul_f32 v[10:11], v[66:67], v[14:15] op_sel:[0,1] op_sel_hi:[1,1]
	v_pk_mul_f32 v[8:9], v[64:65], v[14:15] op_sel:[0,1] op_sel_hi:[1,1]
	v_add_f32_dpp v0, v0, v0 quad_perm:[2,3,0,1] row_mask:0xf bank_mask:0xf bound_ctrl:1
	ds_read_b128 v[44:47], v80 offset:27904
	ds_read_b128 v[48:51], v80 offset:3328
	ds_read_b128 v[52:55], v80 offset:19712
	ds_read_b128 v[56:59], v80 offset:36096
	ds_read_b128 v[60:63], v80 offset:11776
	v_add_f32_e32 v86, v6, v7
	v_add_f32_dpp v0, v0, v0 row_half_mirror row_mask:0xf bank_mask:0xf bound_ctrl:1
	v_pk_fma_f32 v[10:11], v[70:71], v[4:5], v[10:11]
	v_pk_fma_f32 v[8:9], v[68:69], v[2:3], v[8:9]
	v_add_f32_dpp v0, v0, v0 row_mirror row_mask:0xf bank_mask:0xf bound_ctrl:1
	v_pk_fma_f32 v[4:5], v[74:75], v[0:1], v[10:11] op_sel_hi:[1,0,1]
	v_pk_mul_f32 v[6:7], v[22:23], v[4:5]
	v_pk_fma_f32 v[2:3], v[72:73], v[0:1], v[8:9] op_sel_hi:[1,0,1]
	v_pk_fma_f32 v[6:7], v[20:21], v[2:3], v[6:7]
	s_waitcnt lgkmcnt(6)
	v_add_f32_e32 v0, v6, v7
	v_pk_mul_f32 v[6:7], v[78:79], v[4:5]
	v_pk_fma_f32 v[6:7], v[76:77], v[2:3], v[6:7]
	v_add_f32_dpp v0, v0, v0 quad_perm:[1,0,3,2] row_mask:0xf bank_mask:0xf bound_ctrl:1
	v_pk_mul_f32 v[10:11], v[26:27], v[16:17] op_sel_hi:[1,0]
	v_pk_mul_f32 v[8:9], v[24:25], v[16:17] op_sel_hi:[1,0]
	v_add_f32_dpp v0, v0, v0 quad_perm:[2,3,0,1] row_mask:0xf bank_mask:0xf bound_ctrl:1
	ds_read_b128 v[64:67], v80 offset:28160
	ds_read_b128 v[68:71], v80 offset:3584
	ds_read_b128 v[72:75], v80 offset:19968
	ds_read_b128 v[76:79], v80 offset:36352
	ds_read_b128 v[20:23], v80 offset:12032
	v_add_f32_e32 v87, v6, v7
	ds_write2st64_b32 v82, v86, v87 offset0:40 offset1:44
	v_add_f32_dpp v0, v0, v0 row_half_mirror row_mask:0xf bank_mask:0xf bound_ctrl:1
	v_pk_fma_f32 v[10:11], v[30:31], v[4:5], v[10:11]
	v_pk_fma_f32 v[8:9], v[28:29], v[2:3], v[8:9]
	v_add_f32_dpp v0, v0, v0 row_mirror row_mask:0xf bank_mask:0xf bound_ctrl:1
	v_pk_fma_f32 v[4:5], v[34:35], v[0:1], v[10:11] op_sel_hi:[1,0,1]
	v_pk_mul_f32 v[6:7], v[42:43], v[4:5]
	v_pk_fma_f32 v[2:3], v[32:33], v[0:1], v[8:9] op_sel_hi:[1,0,1]
	v_pk_fma_f32 v[6:7], v[40:41], v[2:3], v[6:7]
	s_waitcnt lgkmcnt(6)
	v_add_f32_e32 v0, v6, v7
	v_pk_mul_f32 v[6:7], v[38:39], v[4:5]
	v_pk_fma_f32 v[6:7], v[36:37], v[2:3], v[6:7]
	v_add_f32_dpp v0, v0, v0 quad_perm:[1,0,3,2] row_mask:0xf bank_mask:0xf bound_ctrl:1
	v_pk_mul_f32 v[10:11], v[46:47], v[16:17] op_sel:[0,1] op_sel_hi:[1,1]
	v_pk_mul_f32 v[8:9], v[44:45], v[16:17] op_sel:[0,1] op_sel_hi:[1,1]
	v_add_f32_dpp v0, v0, v0 quad_perm:[2,3,0,1] row_mask:0xf bank_mask:0xf bound_ctrl:1
	ds_read_b128 v[24:27], v80 offset:28416
	ds_read_b128 v[28:31], v80 offset:3840
	ds_read_b128 v[32:35], v80 offset:20224
	ds_read_b128 v[36:39], v80 offset:36608
	ds_read_b128 v[40:43], v80 offset:12288
	ds_read_b128 v[12:15], v81 offset:64
	v_add_f32_e32 v86, v6, v7
	v_add_f32_dpp v0, v0, v0 row_half_mirror row_mask:0xf bank_mask:0xf bound_ctrl:1
	v_pk_fma_f32 v[10:11], v[50:51], v[4:5], v[10:11]
	v_pk_fma_f32 v[8:9], v[48:49], v[2:3], v[8:9]
	v_add_f32_dpp v0, v0, v0 row_mirror row_mask:0xf bank_mask:0xf bound_ctrl:1
	v_pk_fma_f32 v[4:5], v[54:55], v[0:1], v[10:11] op_sel_hi:[1,0,1]
	v_pk_mul_f32 v[6:7], v[62:63], v[4:5]
	v_pk_fma_f32 v[2:3], v[52:53], v[0:1], v[8:9] op_sel_hi:[1,0,1]
	v_pk_fma_f32 v[6:7], v[60:61], v[2:3], v[6:7]
	s_waitcnt lgkmcnt(7)
; #define LAS __attribute__((address_space(3)))
; __device__ __forceinline__ void phase_rwc(const int wvs, const Params& p, LAS unsigned char* lds, int layer, int wg0) {
;     ...
;       for (int t = 0; t < 32; ++t) {
;         const int tn = t + 2;
;         const f32x4 nw4 = *(const LAS f32x4*)(Wv + tn * 64), nkk4 = *(const LAS f32x4*)(Wv + 2048 + tn * 64), nb4 = *(const LAS f32x4*)(Wv + 4096 + tn * 64), nkd4 = *(const LAS f32x4*)(Wv + 6144 + tn * 64), nr4 = *(const LAS f32x4*)(Wv + 8192 + tn * 64);
;         const float nvv = Vv[tn * 16];
;         const f32x4 pa = S * kk4;
;         const f32x4 t1 = S * w4 + vv * kd4;
;         float sa = (pa[0] + pa[2]) + (pa[1] + pa[3]);
;         sa = row16_sum(sa);
;         S = t1 + sa * b4;
;         const f32x4 py = S * r4;
;         ypw[t * 256] = (py[0] + py[2]) + (py[1] + py[3]);
;         w4 = xw4; kk4 = xkk4; b4 = xb4; kd4 = xkd4; r4 = xr4; vv = xvv;
;         xw4 = nw4; xkk4 = nkk4; xb4 = nb4; xkd4 = nkd4; xr4 = nr4; xvv = nvv;
;       }
	v_add_f32_e32 v0, v6, v7
	v_pk_mul_f32 v[6:7], v[58:59], v[4:5]
	v_pk_fma_f32 v[6:7], v[56:57], v[2:3], v[6:7]
	v_add_f32_dpp v0, v0, v0 quad_perm:[1,0,3,2] row_mask:0xf bank_mask:0xf bound_ctrl:1
	v_pk_mul_f32 v[10:11], v[66:67], v[18:19] op_sel_hi:[1,0]
	v_pk_mul_f32 v[8:9], v[64:65], v[18:19] op_sel_hi:[1,0]
	v_add_f32_dpp v0, v0, v0 quad_perm:[2,3,0,1] row_mask:0xf bank_mask:0xf bound_ctrl:1
	ds_read_b128 v[44:47], v80 offset:28672
	ds_read_b128 v[48:51], v80 offset:4096
	ds_read_b128 v[52:55], v80 offset:20480
	ds_read_b128 v[56:59], v80 offset:36864
	ds_read_b128 v[60:63], v80 offset:12544
	v_add_f32_e32 v87, v6, v7
	ds_write2st64_b32 v82, v86, v87 offset0:48 offset1:52
	v_add_f32_dpp v0, v0, v0 row_half_mirror row_mask:0xf bank_mask:0xf bound_ctrl:1
	v_pk_fma_f32 v[10:11], v[70:71], v[4:5], v[10:11]
	v_pk_fma_f32 v[8:9], v[68:69], v[2:3], v[8:9]
	v_add_f32_dpp v0, v0, v0 row_mirror row_mask:0xf bank_mask:0xf bound_ctrl:1
	v_pk_fma_f32 v[4:5], v[74:75], v[0:1], v[10:11] op_sel_hi:[1,0,1]
	v_pk_mul_f32 v[6:7], v[22:23], v[4:5]
	v_pk_fma_f32 v[2:3], v[72:73], v[0:1], v[8:9] op_sel_hi:[1,0,1]
	v_pk_fma_f32 v[6:7], v[20:21], v[2:3], v[6:7]
	s_waitcnt lgkmcnt(7)
	v_add_f32_e32 v0, v6, v7
	v_pk_mul_f32 v[6:7], v[78:79], v[4:5]
	v_pk_fma_f32 v[6:7], v[76:77], v[2:3], v[6:7]
	v_add_f32_dpp v0, v0, v0 quad_perm:[1,0,3,2] row_mask:0xf bank_mask:0xf bound_ctrl:1
	v_pk_mul_f32 v[10:11], v[26:27], v[18:19] op_sel:[0,1] op_sel_hi:[1,1]
	v_pk_mul_f32 v[8:9], v[24:25], v[18:19] op_sel:[0,1] op_sel_hi:[1,1]
	v_add_f32_dpp v0, v0, v0 quad_perm:[2,3,0,1] row_mask:0xf bank_mask:0xf bound_ctrl:1
	ds_read_b128 v[64:67], v80 offset:28928
	ds_read_b128 v[68:71], v80 offset:4352
	ds_read_b128 v[72:75], v80 offset:20736
	ds_read_b128 v[76:79], v80 offset:37120
	ds_read_b128 v[20:23], v80 offset:12800
	v_add_f32_e32 v86, v6, v7
	v_add_f32_dpp v0, v0, v0 row_half_mirror row_mask:0xf bank_mask:0xf bound_ctrl:1
	v_pk_fma_f32 v[10:11], v[30:31], v[4:5], v[10:11]
	v_pk_fma_f32 v[8:9], v[28:29], v[2:3], v[8:9]
	v_add_f32_dpp v0, v0, v0 row_mirror row_mask:0xf bank_mask:0xf bound_ctrl:1
	v_pk_fma_f32 v[4:5], v[34:35], v[0:1], v[10:11] op_sel_hi:[1,0,1]
	v_pk_mul_f32 v[6:7], v[42:43], v[4:5]
	v_pk_fma_f32 v[2:3], v[32:33], v[0:1], v[8:9] op_sel_hi:[1,0,1]
	v_pk_fma_f32 v[6:7], v[40:41], v[2:3], v[6:7]
	s_waitcnt lgkmcnt(6)
	v_add_f32_e32 v0, v6, v7
	v_pk_mul_f32 v[6:7], v[38:39], v[4:5]
	v_pk_fma_f32 v[6:7], v[36:37], v[2:3], v[6:7]
	v_add_f32_dpp v0, v0, v0 quad_perm:[1,0,3,2] row_mask:0xf bank_mask:0xf bound_ctrl:1
	v_pk_mul_f32 v[10:11], v[46:47], v[12:13] op_sel_hi:[1,0]
	v_pk_mul_f32 v[8:9], v[44:45], v[12:13] op_sel_hi:[1,0]
	v_add_f32_dpp v0, v0, v0 quad_perm:[2,3,0,1] row_mask:0xf bank_mask:0xf bound_ctrl:1
	ds_read_b128 v[24:27], v80 offset:29184
	ds_read_b128 v[28:31], v80 offset:4608
	ds_read_b128 v[32:35], v80 offset:20992
	ds_read_b128 v[36:39], v80 offset:37376
	ds_read_b128 v[40:43], v80 offset:13056
	v_add_f32_e32 v87, v6, v7
	ds_write2st64_b32 v82, v86, v87 offset0:56 offset1:60
	v_add_f32_dpp v0, v0, v0 row_half_mirror row_mask:0xf bank_mask:0xf bound_ctrl:1
	v_pk_fma_f32 v[10:11], v[50:51], v[4:5], v[10:11]
	v_pk_fma_f32 v[8:9], v[48:49], v[2:3], v[8:9]
	v_add_f32_dpp v0, v0, v0 row_mirror row_mask:0xf bank_mask:0xf bound_ctrl:1
	v_pk_fma_f32 v[4:5], v[54:55], v[0:1], v[10:11] op_sel_hi:[1,0,1]
	v_pk_mul_f32 v[6:7], v[62:63], v[4:5]
	v_pk_fma_f32 v[2:3], v[52:53], v[0:1], v[8:9] op_sel_hi:[1,0,1]
	v_pk_fma_f32 v[6:7], v[60:61], v[2:3], v[6:7]
	s_waitcnt lgkmcnt(6)
	v_add_f32_e32 v0, v6, v7
	v_pk_mul_f32 v[6:7], v[58:59], v[4:5]
	v_pk_fma_f32 v[6:7], v[56:57], v[2:3], v[6:7]
	v_add_f32_dpp v0, v0, v0 quad_perm:[1,0,3,2] row_mask:0xf bank_mask:0xf bound_ctrl:1
	v_pk_mul_f32 v[10:11], v[66:67], v[12:13] op_sel:[0,1] op_sel_hi:[1,1]
	v_pk_mul_f32 v[8:9], v[64:65], v[12:13] op_sel:[0,1] op_sel_hi:[1,1]
	v_add_f32_dpp v0, v0, v0 quad_perm:[2,3,0,1] row_mask:0xf bank_mask:0xf bound_ctrl:1
	ds_read_b128 v[44:47], v80 offset:29440
	ds_read_b128 v[48:51], v80 offset:4864
	ds_read_b128 v[52:55], v80 offset:21248
	ds_read_b128 v[56:59], v80 offset:37632
	ds_read_b128 v[60:63], v80 offset:13312
	ds_read_b128 v[16:19], v81 offset:80
	v_add_f32_e32 v86, v6, v7
	v_add_f32_dpp v0, v0, v0 row_half_mirror row_mask:0xf bank_mask:0xf bound_ctrl:1
	v_pk_fma_f32 v[10:11], v[70:71], v[4:5], v[10:11]
	v_pk_fma_f32 v[8:9], v[68:69], v[2:3], v[8:9]
	v_add_f32_dpp v0, v0, v0 row_mirror row_mask:0xf bank_mask:0xf bound_ctrl:1
	v_pk_fma_f32 v[4:5], v[74:75], v[0:1], v[10:11] op_sel_hi:[1,0,1]
	v_pk_mul_f32 v[6:7], v[22:23], v[4:5]
	v_pk_fma_f32 v[2:3], v[72:73], v[0:1], v[8:9] op_sel_hi:[1,0,1]
	v_pk_fma_f32 v[6:7], v[20:21], v[2:3], v[6:7]
	s_waitcnt lgkmcnt(7)
	v_add_f32_e32 v0, v6, v7
	v_pk_mul_f32 v[6:7], v[78:79], v[4:5]
	v_pk_fma_f32 v[6:7], v[76:77], v[2:3], v[6:7]
	v_add_f32_dpp v0, v0, v0 quad_perm:[1,0,3,2] row_mask:0xf bank_mask:0xf bound_ctrl:1
	v_pk_mul_f32 v[10:11], v[26:27], v[14:15] op_sel_hi:[1,0]
	v_pk_mul_f32 v[8:9], v[24:25], v[14:15] op_sel_hi:[1,0]
	v_add_f32_dpp v0, v0, v0 quad_perm:[2,3,0,1] row_mask:0xf bank_mask:0xf bound_ctrl:1
	ds_read_b128 v[64:67], v80 offset:29696
	ds_read_b128 v[68:71], v80 offset:5120
	ds_read_b128 v[72:75], v80 offset:21504
	ds_read_b128 v[76:79], v80 offset:37888
	ds_read_b128 v[20:23], v80 offset:13568
	v_add_f32_e32 v87, v6, v7
	ds_write2st64_b32 v82, v86, v87 offset0:64 offset1:68
	v_add_f32_dpp v0, v0, v0 row_half_mirror row_mask:0xf bank_mask:0xf bound_ctrl:1
	v_pk_fma_f32 v[10:11], v[30:31], v[4:5], v[10:11]
	v_pk_fma_f32 v[8:9], v[28:29], v[2:3], v[8:9]
	v_add_f32_dpp v0, v0, v0 row_mirror row_mask:0xf bank_mask:0xf bound_ctrl:1
	v_pk_fma_f32 v[4:5], v[34:35], v[0:1], v[10:11] op_sel_hi:[1,0,1]
	v_pk_mul_f32 v[6:7], v[42:43], v[4:5]
	v_pk_fma_f32 v[2:3], v[32:33], v[0:1], v[8:9] op_sel_hi:[1,0,1]
	v_pk_fma_f32 v[6:7], v[40:41], v[2:3], v[6:7]
	s_waitcnt lgkmcnt(7)
; #define LAS __attribute__((address_space(3)))
; __device__ __forceinline__ void phase_rwc(const int wvs, const Params& p, LAS unsigned char* lds, int layer, int wg0) {
;     ...
;       for (int t = 0; t < 32; ++t) {
;         const int tn = t + 2;
;         const f32x4 nw4 = *(const LAS f32x4*)(Wv + tn * 64), nkk4 = *(const LAS f32x4*)(Wv + 2048 + tn * 64), nb4 = *(const LAS f32x4*)(Wv + 4096 + tn * 64), nkd4 = *(const LAS f32x4*)(Wv + 6144 + tn * 64), nr4 = *(const LAS f32x4*)(Wv + 8192 + tn * 64);
;         const float nvv = Vv[tn * 16];
;         const f32x4 pa = S * kk4;
;         const f32x4 t1 = S * w4 + vv * kd4;
;         float sa = (pa[0] + pa[2]) + (pa[1] + pa[3]);
;         sa = row16_sum(sa);
;         S = t1 + sa * b4;
;         const f32x4 py = S * r4;
;         ypw[t * 256] = (py[0] + py[2]) + (py[1] + py[3]);
;         w4 = xw4; kk4 = xkk4; b4 = xb4; kd4 = xkd4; r4 = xr4; vv = xvv;
;         xw4 = nw4; xkk4 = nkk4; xb4 = nb4; xkd4 = nkd4; xr4 = nr4; xvv = nvv;
;       }
	v_add_f32_e32 v0, v6, v7
	v_pk_mul_f32 v[6:7], v[38:39], v[4:5]
	v_pk_fma_f32 v[6:7], v[36:37], v[2:3], v[6:7]
	v_add_f32_dpp v0, v0, v0 quad_perm:[1,0,3,2] row_mask:0xf bank_mask:0xf bound_ctrl:1
	v_pk_mul_f32 v[10:11], v[46:47], v[14:15] op_sel:[0,1] op_sel_hi:[1,1]
	v_pk_mul_f32 v[8:9], v[44:45], v[14:15] op_sel:[0,1] op_sel_hi:[1,1]
	v_add_f32_dpp v0, v0, v0 quad_perm:[2,3,0,1] row_mask:0xf bank_mask:0xf bound_ctrl:1
	ds_read_b128 v[24:27], v80 offset:29952
	ds_read_b128 v[28:31], v80 offset:5376
	ds_read_b128 v[32:35], v80 offset:21760
	ds_read_b128 v[36:39], v80 offset:38144
	ds_read_b128 v[40:43], v80 offset:13824
	v_add_f32_e32 v86, v6, v7
	v_add_f32_dpp v0, v0, v0 row_half_mirror row_mask:0xf bank_mask:0xf bound_ctrl:1
	v_pk_fma_f32 v[10:11], v[50:51], v[4:5], v[10:11]
	v_pk_fma_f32 v[8:9], v[48:49], v[2:3], v[8:9]
	v_add_f32_dpp v0, v0, v0 row_mirror row_mask:0xf bank_mask:0xf bound_ctrl:1
	v_pk_fma_f32 v[4:5], v[54:55], v[0:1], v[10:11] op_sel_hi:[1,0,1]
	v_pk_mul_f32 v[6:7], v[62:63], v[4:5]
	v_pk_fma_f32 v[2:3], v[52:53], v[0:1], v[8:9] op_sel_hi:[1,0,1]
	v_pk_fma_f32 v[6:7], v[60:61], v[2:3], v[6:7]
	s_waitcnt lgkmcnt(6)
	v_add_f32_e32 v0, v6, v7
	v_pk_mul_f32 v[6:7], v[58:59], v[4:5]
	v_pk_fma_f32 v[6:7], v[56:57], v[2:3], v[6:7]
	v_add_f32_dpp v0, v0, v0 quad_perm:[1,0,3,2] row_mask:0xf bank_mask:0xf bound_ctrl:1
	v_pk_mul_f32 v[10:11], v[66:67], v[16:17] op_sel_hi:[1,0]
	v_pk_mul_f32 v[8:9], v[64:65], v[16:17] op_sel_hi:[1,0]
	v_add_f32_dpp v0, v0, v0 quad_perm:[2,3,0,1] row_mask:0xf bank_mask:0xf bound_ctrl:1
	ds_read_b128 v[44:47], v80 offset:30208
	ds_read_b128 v[48:51], v80 offset:5632
	ds_read_b128 v[52:55], v80 offset:22016
	ds_read_b128 v[56:59], v80 offset:38400
	ds_read_b128 v[60:63], v80 offset:14080
	v_add_f32_e32 v87, v6, v7
	ds_write2st64_b32 v82, v86, v87 offset0:72 offset1:76
	v_add_f32_dpp v0, v0, v0 row_half_mirror row_mask:0xf bank_mask:0xf bound_ctrl:1
	v_pk_fma_f32 v[10:11], v[70:71], v[4:5], v[10:11]
	v_pk_fma_f32 v[8:9], v[68:69], v[2:3], v[8:9]
	v_add_f32_dpp v0, v0, v0 row_mirror row_mask:0xf bank_mask:0xf bound_ctrl:1
	v_pk_fma_f32 v[4:5], v[74:75], v[0:1], v[10:11] op_sel_hi:[1,0,1]
	v_pk_mul_f32 v[6:7], v[22:23], v[4:5]
	v_pk_fma_f32 v[2:3], v[72:73], v[0:1], v[8:9] op_sel_hi:[1,0,1]
	v_pk_fma_f32 v[6:7], v[20:21], v[2:3], v[6:7]
	s_waitcnt lgkmcnt(6)
	v_add_f32_e32 v0, v6, v7
	v_pk_mul_f32 v[6:7], v[78:79], v[4:5]
	v_pk_fma_f32 v[6:7], v[76:77], v[2:3], v[6:7]
	v_add_f32_dpp v0, v0, v0 quad_perm:[1,0,3,2] row_mask:0xf bank_mask:0xf bound_ctrl:1
	v_pk_mul_f32 v[10:11], v[26:27], v[16:17] op_sel:[0,1] op_sel_hi:[1,1]
	v_pk_mul_f32 v[8:9], v[24:25], v[16:17] op_sel:[0,1] op_sel_hi:[1,1]
	v_add_f32_dpp v0, v0, v0 quad_perm:[2,3,0,1] row_mask:0xf bank_mask:0xf bound_ctrl:1
	ds_read_b128 v[64:67], v80 offset:30464
	ds_read_b128 v[68:71], v80 offset:5888
	ds_read_b128 v[72:75], v80 offset:22272
	ds_read_b128 v[76:79], v80 offset:38656
	ds_read_b128 v[20:23], v80 offset:14336
	ds_read_b128 v[12:15], v81 offset:96
	v_add_f32_e32 v86, v6, v7
	v_add_f32_dpp v0, v0, v0 row_half_mirror row_mask:0xf bank_mask:0xf bound_ctrl:1
	v_pk_fma_f32 v[10:11], v[30:31], v[4:5], v[10:11]
	v_pk_fma_f32 v[8:9], v[28:29], v[2:3], v[8:9]
	v_add_f32_dpp v0, v0, v0 row_mirror row_mask:0xf bank_mask:0xf bound_ctrl:1
	v_pk_fma_f32 v[4:5], v[34:35], v[0:1], v[10:11] op_sel_hi:[1,0,1]
	v_pk_mul_f32 v[6:7], v[42:43], v[4:5]
	v_pk_fma_f32 v[2:3], v[32:33], v[0:1], v[8:9] op_sel_hi:[1,0,1]
	v_pk_fma_f32 v[6:7], v[40:41], v[2:3], v[6:7]
	s_waitcnt lgkmcnt(7)
	v_add_f32_e32 v0, v6, v7
	v_pk_mul_f32 v[6:7], v[38:39], v[4:5]
	v_pk_fma_f32 v[6:7], v[36:37], v[2:3], v[6:7]
	v_add_f32_dpp v0, v0, v0 quad_perm:[1,0,3,2] row_mask:0xf bank_mask:0xf bound_ctrl:1
	v_pk_mul_f32 v[10:11], v[46:47], v[18:19] op_sel_hi:[1,0]
	v_pk_mul_f32 v[8:9], v[44:45], v[18:19] op_sel_hi:[1,0]
	v_add_f32_dpp v0, v0, v0 quad_perm:[2,3,0,1] row_mask:0xf bank_mask:0xf bound_ctrl:1
	ds_read_b128 v[24:27], v80 offset:30720
	ds_read_b128 v[28:31], v80 offset:6144
	ds_read_b128 v[32:35], v80 offset:22528
	ds_read_b128 v[36:39], v80 offset:38912
	ds_read_b128 v[40:43], v80 offset:14592
	v_add_f32_e32 v87, v6, v7
	ds_write2st64_b32 v82, v86, v87 offset0:80 offset1:84
	v_add_f32_dpp v0, v0, v0 row_half_mirror row_mask:0xf bank_mask:0xf bound_ctrl:1
	v_pk_fma_f32 v[10:11], v[50:51], v[4:5], v[10:11]
	v_pk_fma_f32 v[8:9], v[48:49], v[2:3], v[8:9]
	v_add_f32_dpp v0, v0, v0 row_mirror row_mask:0xf bank_mask:0xf bound_ctrl:1
	v_pk_fma_f32 v[4:5], v[54:55], v[0:1], v[10:11] op_sel_hi:[1,0,1]
	v_pk_mul_f32 v[6:7], v[62:63], v[4:5]
	v_pk_fma_f32 v[2:3], v[52:53], v[0:1], v[8:9] op_sel_hi:[1,0,1]
	v_pk_fma_f32 v[6:7], v[60:61], v[2:3], v[6:7]
	s_waitcnt lgkmcnt(7)
	v_add_f32_e32 v0, v6, v7
	v_pk_mul_f32 v[6:7], v[58:59], v[4:5]
	v_pk_fma_f32 v[6:7], v[56:57], v[2:3], v[6:7]
	v_add_f32_dpp v0, v0, v0 quad_perm:[1,0,3,2] row_mask:0xf bank_mask:0xf bound_ctrl:1
	v_pk_mul_f32 v[10:11], v[66:67], v[18:19] op_sel:[0,1] op_sel_hi:[1,1]
	v_pk_mul_f32 v[8:9], v[64:65], v[18:19] op_sel:[0,1] op_sel_hi:[1,1]
	v_add_f32_dpp v0, v0, v0 quad_perm:[2,3,0,1] row_mask:0xf bank_mask:0xf bound_ctrl:1
	ds_read_b128 v[44:47], v80 offset:30976
	ds_read_b128 v[48:51], v80 offset:6400
	ds_read_b128 v[52:55], v80 offset:22784
	ds_read_b128 v[56:59], v80 offset:39168
	ds_read_b128 v[60:63], v80 offset:14848
	v_add_f32_e32 v86, v6, v7
	v_add_f32_dpp v0, v0, v0 row_half_mirror row_mask:0xf bank_mask:0xf bound_ctrl:1
	v_pk_fma_f32 v[10:11], v[70:71], v[4:5], v[10:11]
	v_pk_fma_f32 v[8:9], v[68:69], v[2:3], v[8:9]
	v_add_f32_dpp v0, v0, v0 row_mirror row_mask:0xf bank_mask:0xf bound_ctrl:1
	v_pk_fma_f32 v[4:5], v[74:75], v[0:1], v[10:11] op_sel_hi:[1,0,1]
	v_pk_mul_f32 v[6:7], v[22:23], v[4:5]
	v_pk_fma_f32 v[2:3], v[72:73], v[0:1], v[8:9] op_sel_hi:[1,0,1]
	v_pk_fma_f32 v[6:7], v[20:21], v[2:3], v[6:7]
	s_waitcnt lgkmcnt(6)
; #define LAS __attribute__((address_space(3)))
; __device__ __forceinline__ void phase_rwc(const int wvs, const Params& p, LAS unsigned char* lds, int layer, int wg0) {
;     ...
;       for (int t = 0; t < 32; ++t) {
;         const int tn = t + 2;
;         const f32x4 nw4 = *(const LAS f32x4*)(Wv + tn * 64), nkk4 = *(const LAS f32x4*)(Wv + 2048 + tn * 64), nb4 = *(const LAS f32x4*)(Wv + 4096 + tn * 64), nkd4 = *(const LAS f32x4*)(Wv + 6144 + tn * 64), nr4 = *(const LAS f32x4*)(Wv + 8192 + tn * 64);
;         const float nvv = Vv[tn * 16];
;         const f32x4 pa = S * kk4;
;         const f32x4 t1 = S * w4 + vv * kd4;
;         float sa = (pa[0] + pa[2]) + (pa[1] + pa[3]);
;         sa = row16_sum(sa);
;         S = t1 + sa * b4;
;         const f32x4 py = S * r4;
;         ypw[t * 256] = (py[0] + py[2]) + (py[1] + py[3]);
;         w4 = xw4; kk4 = xkk4; b4 = xb4; kd4 = xkd4; r4 = xr4; vv = xvv;
;         xw4 = nw4; xkk4 = nkk4; xb4 = nb4; xkd4 = nkd4; xr4 = nr4; xvv = nvv;
;       }
;       __syncthreads();
	v_add_f32_e32 v0, v6, v7
	v_pk_mul_f32 v[6:7], v[78:79], v[4:5]
	v_pk_fma_f32 v[6:7], v[76:77], v[2:3], v[6:7]
	v_add_f32_dpp v0, v0, v0 quad_perm:[1,0,3,2] row_mask:0xf bank_mask:0xf bound_ctrl:1
	v_pk_mul_f32 v[10:11], v[26:27], v[12:13] op_sel_hi:[1,0]
	v_pk_mul_f32 v[8:9], v[24:25], v[12:13] op_sel_hi:[1,0]
	v_add_f32_dpp v0, v0, v0 quad_perm:[2,3,0,1] row_mask:0xf bank_mask:0xf bound_ctrl:1
	ds_read_b128 v[64:67], v80 offset:31232
	ds_read_b128 v[68:71], v80 offset:6656
	ds_read_b128 v[72:75], v80 offset:23040
	ds_read_b128 v[76:79], v80 offset:39424
	ds_read_b128 v[20:23], v80 offset:15104
	v_add_f32_e32 v87, v6, v7
	ds_write2st64_b32 v82, v86, v87 offset0:88 offset1:92
	v_add_f32_dpp v0, v0, v0 row_half_mirror row_mask:0xf bank_mask:0xf bound_ctrl:1
	v_pk_fma_f32 v[10:11], v[30:31], v[4:5], v[10:11]
	v_pk_fma_f32 v[8:9], v[28:29], v[2:3], v[8:9]
	v_add_f32_dpp v0, v0, v0 row_mirror row_mask:0xf bank_mask:0xf bound_ctrl:1
	v_pk_fma_f32 v[4:5], v[34:35], v[0:1], v[10:11] op_sel_hi:[1,0,1]
	v_pk_mul_f32 v[6:7], v[42:43], v[4:5]
	v_pk_fma_f32 v[2:3], v[32:33], v[0:1], v[8:9] op_sel_hi:[1,0,1]
	v_pk_fma_f32 v[6:7], v[40:41], v[2:3], v[6:7]
	s_waitcnt lgkmcnt(6)
	v_add_f32_e32 v0, v6, v7
	v_pk_mul_f32 v[6:7], v[38:39], v[4:5]
	v_pk_fma_f32 v[6:7], v[36:37], v[2:3], v[6:7]
	v_add_f32_dpp v0, v0, v0 quad_perm:[1,0,3,2] row_mask:0xf bank_mask:0xf bound_ctrl:1
	v_pk_mul_f32 v[10:11], v[46:47], v[12:13] op_sel:[0,1] op_sel_hi:[1,1]
	v_pk_mul_f32 v[8:9], v[44:45], v[12:13] op_sel:[0,1] op_sel_hi:[1,1]
	v_add_f32_dpp v0, v0, v0 quad_perm:[2,3,0,1] row_mask:0xf bank_mask:0xf bound_ctrl:1
	ds_read_b128 v[24:27], v80 offset:31488
	ds_read_b128 v[28:31], v80 offset:6912
	ds_read_b128 v[32:35], v80 offset:23296
	ds_read_b128 v[36:39], v80 offset:39680
	ds_read_b128 v[40:43], v80 offset:15360
	ds_read_b128 v[16:19], v81 offset:112
	v_add_f32_e32 v86, v6, v7
	v_add_f32_dpp v0, v0, v0 row_half_mirror row_mask:0xf bank_mask:0xf bound_ctrl:1
	v_pk_fma_f32 v[10:11], v[50:51], v[4:5], v[10:11]
	v_pk_fma_f32 v[8:9], v[48:49], v[2:3], v[8:9]
	v_add_f32_dpp v0, v0, v0 row_mirror row_mask:0xf bank_mask:0xf bound_ctrl:1
	v_pk_fma_f32 v[4:5], v[54:55], v[0:1], v[10:11] op_sel_hi:[1,0,1]
	v_pk_mul_f32 v[6:7], v[62:63], v[4:5]
	v_pk_fma_f32 v[2:3], v[52:53], v[0:1], v[8:9] op_sel_hi:[1,0,1]
	v_pk_fma_f32 v[6:7], v[60:61], v[2:3], v[6:7]
	s_waitcnt lgkmcnt(7)
	v_add_f32_e32 v0, v6, v7
	v_pk_mul_f32 v[6:7], v[58:59], v[4:5]
	v_pk_fma_f32 v[6:7], v[56:57], v[2:3], v[6:7]
	v_add_f32_dpp v0, v0, v0 quad_perm:[1,0,3,2] row_mask:0xf bank_mask:0xf bound_ctrl:1
	v_pk_mul_f32 v[10:11], v[66:67], v[14:15] op_sel_hi:[1,0]
	v_pk_mul_f32 v[8:9], v[64:65], v[14:15] op_sel_hi:[1,0]
	v_add_f32_dpp v0, v0, v0 quad_perm:[2,3,0,1] row_mask:0xf bank_mask:0xf bound_ctrl:1
	ds_read_b128 v[44:47], v80 offset:31744
	ds_read_b128 v[48:51], v80 offset:7168
	ds_read_b128 v[52:55], v80 offset:23552
	ds_read_b128 v[56:59], v80 offset:39936
	ds_read_b128 v[60:63], v80 offset:15616
	v_add_f32_e32 v87, v6, v7
	ds_write2st64_b32 v82, v86, v87 offset0:96 offset1:100
	v_add_f32_dpp v0, v0, v0 row_half_mirror row_mask:0xf bank_mask:0xf bound_ctrl:1
	v_pk_fma_f32 v[10:11], v[70:71], v[4:5], v[10:11]
	v_pk_fma_f32 v[8:9], v[68:69], v[2:3], v[8:9]
	v_add_f32_dpp v0, v0, v0 row_mirror row_mask:0xf bank_mask:0xf bound_ctrl:1
	v_pk_fma_f32 v[4:5], v[74:75], v[0:1], v[10:11] op_sel_hi:[1,0,1]
	v_pk_mul_f32 v[6:7], v[22:23], v[4:5]
	v_pk_fma_f32 v[2:3], v[72:73], v[0:1], v[8:9] op_sel_hi:[1,0,1]
	v_pk_fma_f32 v[6:7], v[20:21], v[2:3], v[6:7]
	s_waitcnt lgkmcnt(7)
	v_add_f32_e32 v0, v6, v7
	v_pk_mul_f32 v[6:7], v[78:79], v[4:5]
	v_pk_fma_f32 v[6:7], v[76:77], v[2:3], v[6:7]
	v_add_f32_dpp v0, v0, v0 quad_perm:[1,0,3,2] row_mask:0xf bank_mask:0xf bound_ctrl:1
	v_pk_mul_f32 v[10:11], v[26:27], v[14:15] op_sel:[0,1] op_sel_hi:[1,1]
	v_pk_mul_f32 v[8:9], v[24:25], v[14:15] op_sel:[0,1] op_sel_hi:[1,1]
	v_add_f32_dpp v0, v0, v0 quad_perm:[2,3,0,1] row_mask:0xf bank_mask:0xf bound_ctrl:1
	ds_read_b128 v[64:67], v80 offset:32000
	ds_read_b128 v[68:71], v80 offset:7424
	ds_read_b128 v[72:75], v80 offset:23808
	ds_read_b128 v[76:79], v80 offset:40192
	ds_read_b128 v[20:23], v80 offset:15872
	v_add_f32_e32 v86, v6, v7
	v_add_f32_dpp v0, v0, v0 row_half_mirror row_mask:0xf bank_mask:0xf bound_ctrl:1
	v_pk_fma_f32 v[10:11], v[30:31], v[4:5], v[10:11]
	v_pk_fma_f32 v[8:9], v[28:29], v[2:3], v[8:9]
	v_add_f32_dpp v0, v0, v0 row_mirror row_mask:0xf bank_mask:0xf bound_ctrl:1
	v_pk_fma_f32 v[4:5], v[34:35], v[0:1], v[10:11] op_sel_hi:[1,0,1]
	v_pk_mul_f32 v[6:7], v[42:43], v[4:5]
	v_pk_fma_f32 v[2:3], v[32:33], v[0:1], v[8:9] op_sel_hi:[1,0,1]
	v_pk_fma_f32 v[6:7], v[40:41], v[2:3], v[6:7]
	s_waitcnt lgkmcnt(6)
	v_add_f32_e32 v0, v6, v7
	v_pk_mul_f32 v[6:7], v[38:39], v[4:5]
	v_pk_fma_f32 v[6:7], v[36:37], v[2:3], v[6:7]
	v_add_f32_dpp v0, v0, v0 quad_perm:[1,0,3,2] row_mask:0xf bank_mask:0xf bound_ctrl:1
	v_pk_mul_f32 v[10:11], v[46:47], v[16:17] op_sel_hi:[1,0]
	v_pk_mul_f32 v[8:9], v[44:45], v[16:17] op_sel_hi:[1,0]
	v_add_f32_dpp v0, v0, v0 quad_perm:[2,3,0,1] row_mask:0xf bank_mask:0xf bound_ctrl:1
	ds_read_b128 v[24:27], v80 offset:32256
	ds_read_b128 v[28:31], v80 offset:7680
	ds_read_b128 v[32:35], v80 offset:24064
	ds_read_b128 v[36:39], v80 offset:40448
	ds_read_b128 v[40:43], v80 offset:16128
	v_add_f32_e32 v87, v6, v7
	ds_write2st64_b32 v82, v86, v87 offset0:104 offset1:108
	v_add_f32_dpp v0, v0, v0 row_half_mirror row_mask:0xf bank_mask:0xf bound_ctrl:1
	v_pk_fma_f32 v[10:11], v[50:51], v[4:5], v[10:11]
	v_pk_fma_f32 v[8:9], v[48:49], v[2:3], v[8:9]
	v_add_f32_dpp v0, v0, v0 row_mirror row_mask:0xf bank_mask:0xf bound_ctrl:1
	v_pk_fma_f32 v[4:5], v[54:55], v[0:1], v[10:11] op_sel_hi:[1,0,1]
	v_pk_mul_f32 v[6:7], v[62:63], v[4:5]
	v_pk_fma_f32 v[2:3], v[52:53], v[0:1], v[8:9] op_sel_hi:[1,0,1]
	v_pk_fma_f32 v[6:7], v[60:61], v[2:3], v[6:7]
	s_waitcnt lgkmcnt(6)
; #define LAS __attribute__((address_space(3)))
; __device__ __forceinline__ void phase_rwc(const int wvs, const Params& p, LAS unsigned char* lds, int layer, int wg0) {
;     ...
; #pragma unroll 2
;     for (int blk = 0; blk < NBLK; ++blk) {
;       LAS float* Wv = (LAS float*)(lds + (blk & 1) * BUFSZ) + kg * 4; LAS float* Vv = (LAS float*)(lds + (blk & 1) * BUFSZ) + 5 * 2048 + rowl;
;       LAS float* ypw = (LAS float*)(lds + YOFF + (blk & 1) * YSZ) + rowl * 16 + kg;
;       asm volatile("" : "+v"(Wv), "+v"(Vv), "+v"(ypw));
;       f32x4 w4 = *(const LAS f32x4*)(Wv), kk4 = *(const LAS f32x4*)(Wv + 2048), b4 = *(const LAS f32x4*)(Wv + 4096), kd4 = *(const LAS f32x4*)(Wv + 6144), r4 = *(const LAS f32x4*)(Wv + 8192); float vv = Vv[0];
;       f32x4 xw4 = *(const LAS f32x4*)(Wv + 64), xkk4 = *(const LAS f32x4*)(Wv + 2048 + 64), xb4 = *(const LAS f32x4*)(Wv + 4096 + 64), xkd4 = *(const LAS f32x4*)(Wv + 6144 + 64), xr4 = *(const LAS f32x4*)(Wv + 8192 + 64); float xvv = Vv[16];
; #pragma unroll 16
;       for (int t = 0; t < 32; ++t) {
;         const int tn = t + 2;
;         const f32x4 nw4 = *(const LAS f32x4*)(Wv + tn * 64), nkk4 = *(const LAS f32x4*)(Wv + 2048 + tn * 64), nb4 = *(const LAS f32x4*)(Wv + 4096 + tn * 64), nkd4 = *(const LAS f32x4*)(Wv + 6144 + tn * 64), nr4 = *(const LAS f32x4*)(Wv + 8192 + tn * 64);
;         const float nvv = Vv[tn * 16];
;         const f32x4 pa = S * kk4;
;         const f32x4 t1 = S * w4 + vv * kd4;
;         float sa = (pa[0] + pa[2]) + (pa[1] + pa[3]);
;         sa = row16_sum(sa);
;         S = t1 + sa * b4;
;         const f32x4 py = S * r4;
;         ypw[t * 256] = (py[0] + py[2]) + (py[1] + py[3]);
;         w4 = xw4; kk4 = xkk4; b4 = xb4; kd4 = xkd4; r4 = xr4; vv = xvv;
;         xw4 = nw4; xkk4 = nkk4; xb4 = nb4; xkd4 = nkd4; xr4 = nr4; xvv = nvv;
;       }
;       __syncthreads();
	v_add_f32_e32 v0, v6, v7
	v_pk_mul_f32 v[6:7], v[58:59], v[4:5]
	v_pk_fma_f32 v[6:7], v[56:57], v[2:3], v[6:7]
	v_add_f32_dpp v0, v0, v0 quad_perm:[1,0,3,2] row_mask:0xf bank_mask:0xf bound_ctrl:1
	v_pk_mul_f32 v[10:11], v[66:67], v[16:17] op_sel:[0,1] op_sel_hi:[1,1]
	v_pk_mul_f32 v[8:9], v[64:65], v[16:17] op_sel:[0,1] op_sel_hi:[1,1]
	v_add_f32_dpp v0, v0, v0 quad_perm:[2,3,0,1] row_mask:0xf bank_mask:0xf bound_ctrl:1
	ds_read_b128 v[44:47], v80 offset:32512
	ds_read_b128 v[48:51], v80 offset:7936
	ds_read_b128 v[52:55], v80 offset:24320
	ds_read_b128 v[56:59], v80 offset:40704
	v_add_f32_e32 v86, v6, v7
	v_add_f32_dpp v0, v0, v0 row_half_mirror row_mask:0xf bank_mask:0xf bound_ctrl:1
	v_pk_fma_f32 v[10:11], v[70:71], v[4:5], v[10:11]
	v_pk_fma_f32 v[8:9], v[68:69], v[2:3], v[8:9]
	v_add_f32_dpp v0, v0, v0 row_mirror row_mask:0xf bank_mask:0xf bound_ctrl:1
	v_pk_fma_f32 v[4:5], v[74:75], v[0:1], v[10:11] op_sel_hi:[1,0,1]
	v_pk_mul_f32 v[6:7], v[22:23], v[4:5]
	v_pk_fma_f32 v[2:3], v[72:73], v[0:1], v[8:9] op_sel_hi:[1,0,1]
	v_pk_fma_f32 v[6:7], v[20:21], v[2:3], v[6:7]
	s_waitcnt lgkmcnt(5)
	v_add_f32_e32 v0, v6, v7
	v_pk_mul_f32 v[6:7], v[78:79], v[4:5]
	v_pk_fma_f32 v[6:7], v[76:77], v[2:3], v[6:7]
	v_add_f32_dpp v0, v0, v0 quad_perm:[1,0,3,2] row_mask:0xf bank_mask:0xf bound_ctrl:1
	v_pk_mul_f32 v[10:11], v[26:27], v[18:19] op_sel_hi:[1,0]
	v_pk_mul_f32 v[8:9], v[24:25], v[18:19] op_sel_hi:[1,0]
	v_add_f32_dpp v0, v0, v0 quad_perm:[2,3,0,1] row_mask:0xf bank_mask:0xf bound_ctrl:1
	v_add_f32_e32 v87, v6, v7
	ds_write2st64_b32 v82, v86, v87 offset0:112 offset1:116
	v_add_f32_dpp v0, v0, v0 row_half_mirror row_mask:0xf bank_mask:0xf bound_ctrl:1
	v_pk_fma_f32 v[10:11], v[30:31], v[4:5], v[10:11]
	v_pk_fma_f32 v[8:9], v[28:29], v[2:3], v[8:9]
	v_add_f32_dpp v0, v0, v0 row_mirror row_mask:0xf bank_mask:0xf bound_ctrl:1
	v_pk_fma_f32 v[4:5], v[34:35], v[0:1], v[10:11] op_sel_hi:[1,0,1]
	v_pk_mul_f32 v[6:7], v[42:43], v[4:5]
	v_pk_fma_f32 v[2:3], v[32:33], v[0:1], v[8:9] op_sel_hi:[1,0,1]
	v_pk_fma_f32 v[6:7], v[40:41], v[2:3], v[6:7]
	s_waitcnt lgkmcnt(1)
	v_add_f32_e32 v0, v6, v7
	v_pk_mul_f32 v[6:7], v[38:39], v[4:5]
	v_pk_fma_f32 v[6:7], v[36:37], v[2:3], v[6:7]
	v_add_f32_dpp v0, v0, v0 quad_perm:[1,0,3,2] row_mask:0xf bank_mask:0xf bound_ctrl:1
	v_pk_mul_f32 v[10:11], v[46:47], v[18:19] op_sel:[0,1] op_sel_hi:[1,1]
	v_pk_mul_f32 v[8:9], v[44:45], v[18:19] op_sel:[0,1] op_sel_hi:[1,1]
	v_add_f32_dpp v0, v0, v0 quad_perm:[2,3,0,1] row_mask:0xf bank_mask:0xf bound_ctrl:1
	v_add_f32_e32 v86, v6, v7
	s_nop 0
	v_add_f32_dpp v0, v0, v0 row_half_mirror row_mask:0xf bank_mask:0xf bound_ctrl:1
	v_pk_fma_f32 v[10:11], v[50:51], v[4:5], v[10:11]
	v_pk_fma_f32 v[8:9], v[48:49], v[2:3], v[8:9]
	v_add_f32_dpp v0, v0, v0 row_mirror row_mask:0xf bank_mask:0xf bound_ctrl:1
	v_pk_fma_f32 v[4:5], v[54:55], v[0:1], v[10:11] op_sel_hi:[1,0,1]
	v_pk_fma_f32 v[2:3], v[52:53], v[0:1], v[8:9] op_sel_hi:[1,0,1]
	v_pk_mul_f32 v[6:7], v[58:59], v[4:5]
	v_pk_fma_f32 v[6:7], v[56:57], v[2:3], v[6:7]
	s_nop 0
	v_add_f32_e32 v87, v6, v7
	ds_write2st64_b32 v82, v86, v87 offset0:120 offset1:124
	s_waitcnt lgkmcnt(0)
	s_barrier
	ds_read_b128 v[20:23], v83 offset:8192
	ds_read_b128 v[24:27], v83 offset:24576
	ds_read_b128 v[12:15], v84 offset:0
	ds_read_b128 v[28:31], v83 offset:0
	ds_read_b128 v[32:35], v83 offset:16384
	ds_read_b128 v[36:39], v83 offset:32768
	ds_read_b128 v[40:43], v83 offset:8448
	ds_read_b128 v[44:47], v83 offset:24832
	ds_read_b128 v[48:51], v83 offset:256
	ds_read_b128 v[52:55], v83 offset:16640
	ds_read_b128 v[56:59], v83 offset:33024
	ds_read_b128 v[60:63], v83 offset:8704
	s_waitcnt lgkmcnt(11)
	v_pk_mul_f32 v[6:7], v[22:23], v[4:5]
	v_pk_fma_f32 v[6:7], v[20:21], v[2:3], v[6:7]
	s_waitcnt lgkmcnt(6)
	v_add_f32_e32 v0, v6, v7
	v_pk_mul_f32 v[10:11], v[26:27], v[12:13] op_sel_hi:[1,0]
	v_pk_mul_f32 v[8:9], v[24:25], v[12:13] op_sel_hi:[1,0]
	v_add_f32_dpp v0, v0, v0 quad_perm:[1,0,3,2] row_mask:0xf bank_mask:0xf bound_ctrl:1
	v_pk_fma_f32 v[10:11], v[30:31], v[4:5], v[10:11]
	v_pk_fma_f32 v[8:9], v[28:29], v[2:3], v[8:9]
	v_add_f32_dpp v0, v0, v0 quad_perm:[2,3,0,1] row_mask:0xf bank_mask:0xf bound_ctrl:1
	ds_read_b128 v[64:67], v83 offset:25088
	ds_read_b128 v[68:71], v83 offset:512
	ds_read_b128 v[72:75], v83 offset:16896
	ds_read_b128 v[76:79], v83 offset:33280
	ds_read_b128 v[20:23], v83 offset:8960
	v_add_f32_dpp v0, v0, v0 row_half_mirror row_mask:0xf bank_mask:0xf bound_ctrl:1
	s_nop 1
	v_add_f32_dpp v0, v0, v0 row_mirror row_mask:0xf bank_mask:0xf bound_ctrl:1
	v_pk_fma_f32 v[4:5], v[34:35], v[0:1], v[10:11] op_sel_hi:[1,0,1]
	s_waitcnt lgkmcnt(10)
	v_pk_mul_f32 v[6:7], v[42:43], v[4:5]
	v_pk_fma_f32 v[2:3], v[32:33], v[0:1], v[8:9] op_sel_hi:[1,0,1]
	v_pk_fma_f32 v[6:7], v[40:41], v[2:3], v[6:7]
	s_waitcnt lgkmcnt(5)
	v_add_f32_e32 v0, v6, v7
	v_pk_mul_f32 v[6:7], v[38:39], v[4:5]
	v_pk_fma_f32 v[6:7], v[36:37], v[2:3], v[6:7]
	v_add_f32_dpp v0, v0, v0 quad_perm:[1,0,3,2] row_mask:0xf bank_mask:0xf bound_ctrl:1
	v_pk_mul_f32 v[10:11], v[46:47], v[12:13] op_sel:[0,1] op_sel_hi:[1,1]
	v_pk_mul_f32 v[8:9], v[44:45], v[12:13] op_sel:[0,1] op_sel_hi:[1,1]
	v_add_f32_dpp v0, v0, v0 quad_perm:[2,3,0,1] row_mask:0xf bank_mask:0xf bound_ctrl:1
	ds_read_b128 v[24:27], v83 offset:25344
	ds_read_b128 v[28:31], v83 offset:768
	ds_read_b128 v[32:35], v83 offset:17152
	ds_read_b128 v[36:39], v83 offset:33536
	ds_read_b128 v[40:43], v83 offset:9216
	ds_read_b128 v[16:19], v84 offset:16
	v_add_f32_e32 v86, v6, v7
	v_add_f32_dpp v0, v0, v0 row_half_mirror row_mask:0xf bank_mask:0xf bound_ctrl:1
	v_pk_fma_f32 v[10:11], v[50:51], v[4:5], v[10:11]
	v_pk_fma_f32 v[8:9], v[48:49], v[2:3], v[8:9]
	v_add_f32_dpp v0, v0, v0 row_mirror row_mask:0xf bank_mask:0xf bound_ctrl:1
	v_pk_fma_f32 v[4:5], v[54:55], v[0:1], v[10:11] op_sel_hi:[1,0,1]
	v_pk_mul_f32 v[6:7], v[62:63], v[4:5]
	v_pk_fma_f32 v[2:3], v[52:53], v[0:1], v[8:9] op_sel_hi:[1,0,1]
	v_pk_fma_f32 v[6:7], v[60:61], v[2:3], v[6:7]
	s_waitcnt lgkmcnt(6)
; #define LAS __attribute__((address_space(3)))
; __device__ __forceinline__ void phase_rwc(const int wvs, const Params& p, LAS unsigned char* lds, int layer, int wg0) {
;     ...
;       for (int t = 0; t < 32; ++t) {
;         const int tn = t + 2;
;         const f32x4 nw4 = *(const LAS f32x4*)(Wv + tn * 64), nkk4 = *(const LAS f32x4*)(Wv + 2048 + tn * 64), nb4 = *(const LAS f32x4*)(Wv + 4096 + tn * 64), nkd4 = *(const LAS f32x4*)(Wv + 6144 + tn * 64), nr4 = *(const LAS f32x4*)(Wv + 8192 + tn * 64);
;         const float nvv = Vv[tn * 16];
;         const f32x4 pa = S * kk4;
;         const f32x4 t1 = S * w4 + vv * kd4;
;         float sa = (pa[0] + pa[2]) + (pa[1] + pa[3]);
;         sa = row16_sum(sa);
;         S = t1 + sa * b4;
;         const f32x4 py = S * r4;
;         ypw[t * 256] = (py[0] + py[2]) + (py[1] + py[3]);
;         w4 = xw4; kk4 = xkk4; b4 = xb4; kd4 = xkd4; r4 = xr4; vv = xvv;
;         xw4 = nw4; xkk4 = nkk4; xb4 = nb4; xkd4 = nkd4; xr4 = nr4; xvv = nvv;
;       }
	v_add_f32_e32 v0, v6, v7
	v_pk_mul_f32 v[6:7], v[58:59], v[4:5]
	v_pk_fma_f32 v[6:7], v[56:57], v[2:3], v[6:7]
	v_add_f32_dpp v0, v0, v0 quad_perm:[1,0,3,2] row_mask:0xf bank_mask:0xf bound_ctrl:1
	v_pk_mul_f32 v[10:11], v[66:67], v[14:15] op_sel_hi:[1,0]
	v_pk_mul_f32 v[8:9], v[64:65], v[14:15] op_sel_hi:[1,0]
	v_add_f32_dpp v0, v0, v0 quad_perm:[2,3,0,1] row_mask:0xf bank_mask:0xf bound_ctrl:1
	ds_read_b128 v[44:47], v83 offset:25600
	ds_read_b128 v[48:51], v83 offset:1024
	ds_read_b128 v[52:55], v83 offset:17408
	ds_read_b128 v[56:59], v83 offset:33792
	ds_read_b128 v[60:63], v83 offset:9472
	v_add_f32_e32 v87, v6, v7
	ds_write2st64_b32 v85, v86, v87 offset0:0 offset1:4
	v_add_f32_dpp v0, v0, v0 row_half_mirror row_mask:0xf bank_mask:0xf bound_ctrl:1
	v_pk_fma_f32 v[10:11], v[70:71], v[4:5], v[10:11]
	v_pk_fma_f32 v[8:9], v[68:69], v[2:3], v[8:9]
	v_add_f32_dpp v0, v0, v0 row_mirror row_mask:0xf bank_mask:0xf bound_ctrl:1
	v_pk_fma_f32 v[4:5], v[74:75], v[0:1], v[10:11] op_sel_hi:[1,0,1]
	v_pk_mul_f32 v[6:7], v[22:23], v[4:5]
	v_pk_fma_f32 v[2:3], v[72:73], v[0:1], v[8:9] op_sel_hi:[1,0,1]
	v_pk_fma_f32 v[6:7], v[20:21], v[2:3], v[6:7]
	s_waitcnt lgkmcnt(7)
	v_add_f32_e32 v0, v6, v7
	v_pk_mul_f32 v[6:7], v[78:79], v[4:5]
	v_pk_fma_f32 v[6:7], v[76:77], v[2:3], v[6:7]
	v_add_f32_dpp v0, v0, v0 quad_perm:[1,0,3,2] row_mask:0xf bank_mask:0xf bound_ctrl:1
	v_pk_mul_f32 v[10:11], v[26:27], v[14:15] op_sel:[0,1] op_sel_hi:[1,1]
	v_pk_mul_f32 v[8:9], v[24:25], v[14:15] op_sel:[0,1] op_sel_hi:[1,1]
	v_add_f32_dpp v0, v0, v0 quad_perm:[2,3,0,1] row_mask:0xf bank_mask:0xf bound_ctrl:1
	ds_read_b128 v[64:67], v83 offset:25856
	ds_read_b128 v[68:71], v83 offset:1280
	ds_read_b128 v[72:75], v83 offset:17664
	ds_read_b128 v[76:79], v83 offset:34048
	ds_read_b128 v[20:23], v83 offset:9728
	v_add_f32_e32 v86, v6, v7
	v_add_f32_dpp v0, v0, v0 row_half_mirror row_mask:0xf bank_mask:0xf bound_ctrl:1
	v_pk_fma_f32 v[10:11], v[30:31], v[4:5], v[10:11]
	v_pk_fma_f32 v[8:9], v[28:29], v[2:3], v[8:9]
	v_add_f32_dpp v0, v0, v0 row_mirror row_mask:0xf bank_mask:0xf bound_ctrl:1
	v_pk_fma_f32 v[4:5], v[34:35], v[0:1], v[10:11] op_sel_hi:[1,0,1]
	v_pk_mul_f32 v[6:7], v[42:43], v[4:5]
	v_pk_fma_f32 v[2:3], v[32:33], v[0:1], v[8:9] op_sel_hi:[1,0,1]
	v_pk_fma_f32 v[6:7], v[40:41], v[2:3], v[6:7]
	s_waitcnt lgkmcnt(6)
	v_add_f32_e32 v0, v6, v7
	v_pk_mul_f32 v[6:7], v[38:39], v[4:5]
	v_pk_fma_f32 v[6:7], v[36:37], v[2:3], v[6:7]
	v_add_f32_dpp v0, v0, v0 quad_perm:[1,0,3,2] row_mask:0xf bank_mask:0xf bound_ctrl:1
	v_pk_mul_f32 v[10:11], v[46:47], v[16:17] op_sel_hi:[1,0]
	v_pk_mul_f32 v[8:9], v[44:45], v[16:17] op_sel_hi:[1,0]
	v_add_f32_dpp v0, v0, v0 quad_perm:[2,3,0,1] row_mask:0xf bank_mask:0xf bound_ctrl:1
	ds_read_b128 v[24:27], v83 offset:26112
	ds_read_b128 v[28:31], v83 offset:1536
	ds_read_b128 v[32:35], v83 offset:17920
	ds_read_b128 v[36:39], v83 offset:34304
	ds_read_b128 v[40:43], v83 offset:9984
	v_add_f32_e32 v87, v6, v7
	ds_write2st64_b32 v85, v86, v87 offset0:8 offset1:12
	v_add_f32_dpp v0, v0, v0 row_half_mirror row_mask:0xf bank_mask:0xf bound_ctrl:1
	v_pk_fma_f32 v[10:11], v[50:51], v[4:5], v[10:11]
	v_pk_fma_f32 v[8:9], v[48:49], v[2:3], v[8:9]
	v_add_f32_dpp v0, v0, v0 row_mirror row_mask:0xf bank_mask:0xf bound_ctrl:1
	v_pk_fma_f32 v[4:5], v[54:55], v[0:1], v[10:11] op_sel_hi:[1,0,1]
	v_pk_mul_f32 v[6:7], v[62:63], v[4:5]
	v_pk_fma_f32 v[2:3], v[52:53], v[0:1], v[8:9] op_sel_hi:[1,0,1]
	v_pk_fma_f32 v[6:7], v[60:61], v[2:3], v[6:7]
	s_waitcnt lgkmcnt(6)
	v_add_f32_e32 v0, v6, v7
	v_pk_mul_f32 v[6:7], v[58:59], v[4:5]
	v_pk_fma_f32 v[6:7], v[56:57], v[2:3], v[6:7]
	v_add_f32_dpp v0, v0, v0 quad_perm:[1,0,3,2] row_mask:0xf bank_mask:0xf bound_ctrl:1
	v_pk_mul_f32 v[10:11], v[66:67], v[16:17] op_sel:[0,1] op_sel_hi:[1,1]
	v_pk_mul_f32 v[8:9], v[64:65], v[16:17] op_sel:[0,1] op_sel_hi:[1,1]
	v_add_f32_dpp v0, v0, v0 quad_perm:[2,3,0,1] row_mask:0xf bank_mask:0xf bound_ctrl:1
	ds_read_b128 v[44:47], v83 offset:26368
	ds_read_b128 v[48:51], v83 offset:1792
	ds_read_b128 v[52:55], v83 offset:18176
	ds_read_b128 v[56:59], v83 offset:34560
	ds_read_b128 v[60:63], v83 offset:10240
	ds_read_b128 v[12:15], v84 offset:32
	v_add_f32_e32 v86, v6, v7
	v_add_f32_dpp v0, v0, v0 row_half_mirror row_mask:0xf bank_mask:0xf bound_ctrl:1
	v_pk_fma_f32 v[10:11], v[70:71], v[4:5], v[10:11]
	v_pk_fma_f32 v[8:9], v[68:69], v[2:3], v[8:9]
	v_add_f32_dpp v0, v0, v0 row_mirror row_mask:0xf bank_mask:0xf bound_ctrl:1
	v_pk_fma_f32 v[4:5], v[74:75], v[0:1], v[10:11] op_sel_hi:[1,0,1]
	v_pk_mul_f32 v[6:7], v[22:23], v[4:5]
	v_pk_fma_f32 v[2:3], v[72:73], v[0:1], v[8:9] op_sel_hi:[1,0,1]
	v_pk_fma_f32 v[6:7], v[20:21], v[2:3], v[6:7]
	s_waitcnt lgkmcnt(7)
	v_add_f32_e32 v0, v6, v7
	v_pk_mul_f32 v[6:7], v[78:79], v[4:5]
	v_pk_fma_f32 v[6:7], v[76:77], v[2:3], v[6:7]
	v_add_f32_dpp v0, v0, v0 quad_perm:[1,0,3,2] row_mask:0xf bank_mask:0xf bound_ctrl:1
	v_pk_mul_f32 v[10:11], v[26:27], v[18:19] op_sel_hi:[1,0]
	v_pk_mul_f32 v[8:9], v[24:25], v[18:19] op_sel_hi:[1,0]
	v_add_f32_dpp v0, v0, v0 quad_perm:[2,3,0,1] row_mask:0xf bank_mask:0xf bound_ctrl:1
	ds_read_b128 v[64:67], v83 offset:26624
	ds_read_b128 v[68:71], v83 offset:2048
	ds_read_b128 v[72:75], v83 offset:18432
	ds_read_b128 v[76:79], v83 offset:34816
	ds_read_b128 v[20:23], v83 offset:10496
	v_add_f32_e32 v87, v6, v7
	ds_write2st64_b32 v85, v86, v87 offset0:16 offset1:20
	v_add_f32_dpp v0, v0, v0 row_half_mirror row_mask:0xf bank_mask:0xf bound_ctrl:1
	v_pk_fma_f32 v[10:11], v[30:31], v[4:5], v[10:11]
	v_pk_fma_f32 v[8:9], v[28:29], v[2:3], v[8:9]
	v_add_f32_dpp v0, v0, v0 row_mirror row_mask:0xf bank_mask:0xf bound_ctrl:1
	v_pk_fma_f32 v[4:5], v[34:35], v[0:1], v[10:11] op_sel_hi:[1,0,1]
	v_pk_mul_f32 v[6:7], v[42:43], v[4:5]
	v_pk_fma_f32 v[2:3], v[32:33], v[0:1], v[8:9] op_sel_hi:[1,0,1]
	v_pk_fma_f32 v[6:7], v[40:41], v[2:3], v[6:7]
	s_waitcnt lgkmcnt(7)
; #define LAS __attribute__((address_space(3)))
; __device__ __forceinline__ void phase_rwc(const int wvs, const Params& p, LAS unsigned char* lds, int layer, int wg0) {
;     ...
;       for (int t = 0; t < 32; ++t) {
;         const int tn = t + 2;
;         const f32x4 nw4 = *(const LAS f32x4*)(Wv + tn * 64), nkk4 = *(const LAS f32x4*)(Wv + 2048 + tn * 64), nb4 = *(const LAS f32x4*)(Wv + 4096 + tn * 64), nkd4 = *(const LAS f32x4*)(Wv + 6144 + tn * 64), nr4 = *(const LAS f32x4*)(Wv + 8192 + tn * 64);
;         const float nvv = Vv[tn * 16];
;         const f32x4 pa = S * kk4;
;         const f32x4 t1 = S * w4 + vv * kd4;
;         float sa = (pa[0] + pa[2]) + (pa[1] + pa[3]);
;         sa = row16_sum(sa);
;         S = t1 + sa * b4;
;         const f32x4 py = S * r4;
;         ypw[t * 256] = (py[0] + py[2]) + (py[1] + py[3]);
;         w4 = xw4; kk4 = xkk4; b4 = xb4; kd4 = xkd4; r4 = xr4; vv = xvv;
;         xw4 = nw4; xkk4 = nkk4; xb4 = nb4; xkd4 = nkd4; xr4 = nr4; xvv = nvv;
;       }
	v_add_f32_e32 v0, v6, v7
	v_pk_mul_f32 v[6:7], v[38:39], v[4:5]
	v_pk_fma_f32 v[6:7], v[36:37], v[2:3], v[6:7]
	v_add_f32_dpp v0, v0, v0 quad_perm:[1,0,3,2] row_mask:0xf bank_mask:0xf bound_ctrl:1
	v_pk_mul_f32 v[10:11], v[46:47], v[18:19] op_sel:[0,1] op_sel_hi:[1,1]
	v_pk_mul_f32 v[8:9], v[44:45], v[18:19] op_sel:[0,1] op_sel_hi:[1,1]
	v_add_f32_dpp v0, v0, v0 quad_perm:[2,3,0,1] row_mask:0xf bank_mask:0xf bound_ctrl:1
	ds_read_b128 v[24:27], v83 offset:26880
	ds_read_b128 v[28:31], v83 offset:2304
	ds_read_b128 v[32:35], v83 offset:18688
	ds_read_b128 v[36:39], v83 offset:35072
	ds_read_b128 v[40:43], v83 offset:10752
	v_add_f32_e32 v86, v6, v7
	v_add_f32_dpp v0, v0, v0 row_half_mirror row_mask:0xf bank_mask:0xf bound_ctrl:1
	v_pk_fma_f32 v[10:11], v[50:51], v[4:5], v[10:11]
	v_pk_fma_f32 v[8:9], v[48:49], v[2:3], v[8:9]
	v_add_f32_dpp v0, v0, v0 row_mirror row_mask:0xf bank_mask:0xf bound_ctrl:1
	v_pk_fma_f32 v[4:5], v[54:55], v[0:1], v[10:11] op_sel_hi:[1,0,1]
	v_pk_mul_f32 v[6:7], v[62:63], v[4:5]
	v_pk_fma_f32 v[2:3], v[52:53], v[0:1], v[8:9] op_sel_hi:[1,0,1]
	v_pk_fma_f32 v[6:7], v[60:61], v[2:3], v[6:7]
	s_waitcnt lgkmcnt(6)
	v_add_f32_e32 v0, v6, v7
	v_pk_mul_f32 v[6:7], v[58:59], v[4:5]
	v_pk_fma_f32 v[6:7], v[56:57], v[2:3], v[6:7]
	v_add_f32_dpp v0, v0, v0 quad_perm:[1,0,3,2] row_mask:0xf bank_mask:0xf bound_ctrl:1
	v_pk_mul_f32 v[10:11], v[66:67], v[12:13] op_sel_hi:[1,0]
	v_pk_mul_f32 v[8:9], v[64:65], v[12:13] op_sel_hi:[1,0]
	v_add_f32_dpp v0, v0, v0 quad_perm:[2,3,0,1] row_mask:0xf bank_mask:0xf bound_ctrl:1
	ds_read_b128 v[44:47], v83 offset:27136
	ds_read_b128 v[48:51], v83 offset:2560
	ds_read_b128 v[52:55], v83 offset:18944
	ds_read_b128 v[56:59], v83 offset:35328
	ds_read_b128 v[60:63], v83 offset:11008
	v_add_f32_e32 v87, v6, v7
	ds_write2st64_b32 v85, v86, v87 offset0:24 offset1:28
	v_add_f32_dpp v0, v0, v0 row_half_mirror row_mask:0xf bank_mask:0xf bound_ctrl:1
	v_pk_fma_f32 v[10:11], v[70:71], v[4:5], v[10:11]
	v_pk_fma_f32 v[8:9], v[68:69], v[2:3], v[8:9]
	v_add_f32_dpp v0, v0, v0 row_mirror row_mask:0xf bank_mask:0xf bound_ctrl:1
	v_pk_fma_f32 v[4:5], v[74:75], v[0:1], v[10:11] op_sel_hi:[1,0,1]
	v_pk_mul_f32 v[6:7], v[22:23], v[4:5]
	v_pk_fma_f32 v[2:3], v[72:73], v[0:1], v[8:9] op_sel_hi:[1,0,1]
	v_pk_fma_f32 v[6:7], v[20:21], v[2:3], v[6:7]
	s_waitcnt lgkmcnt(6)
	v_add_f32_e32 v0, v6, v7
	v_pk_mul_f32 v[6:7], v[78:79], v[4:5]
	v_pk_fma_f32 v[6:7], v[76:77], v[2:3], v[6:7]
	v_add_f32_dpp v0, v0, v0 quad_perm:[1,0,3,2] row_mask:0xf bank_mask:0xf bound_ctrl:1
	v_pk_mul_f32 v[10:11], v[26:27], v[12:13] op_sel:[0,1] op_sel_hi:[1,1]
	v_pk_mul_f32 v[8:9], v[24:25], v[12:13] op_sel:[0,1] op_sel_hi:[1,1]
	v_add_f32_dpp v0, v0, v0 quad_perm:[2,3,0,1] row_mask:0xf bank_mask:0xf bound_ctrl:1
	ds_read_b128 v[64:67], v83 offset:27392
	ds_read_b128 v[68:71], v83 offset:2816
	ds_read_b128 v[72:75], v83 offset:19200
	ds_read_b128 v[76:79], v83 offset:35584
	ds_read_b128 v[20:23], v83 offset:11264
	ds_read_b128 v[16:19], v84 offset:48
	v_add_f32_e32 v86, v6, v7
	v_add_f32_dpp v0, v0, v0 row_half_mirror row_mask:0xf bank_mask:0xf bound_ctrl:1
	v_pk_fma_f32 v[10:11], v[30:31], v[4:5], v[10:11]
	v_pk_fma_f32 v[8:9], v[28:29], v[2:3], v[8:9]
	v_add_f32_dpp v0, v0, v0 row_mirror row_mask:0xf bank_mask:0xf bound_ctrl:1
	v_pk_fma_f32 v[4:5], v[34:35], v[0:1], v[10:11] op_sel_hi:[1,0,1]
	v_pk_mul_f32 v[6:7], v[42:43], v[4:5]
	v_pk_fma_f32 v[2:3], v[32:33], v[0:1], v[8:9] op_sel_hi:[1,0,1]
	v_pk_fma_f32 v[6:7], v[40:41], v[2:3], v[6:7]
	s_waitcnt lgkmcnt(7)
	v_add_f32_e32 v0, v6, v7
	v_pk_mul_f32 v[6:7], v[38:39], v[4:5]
	v_pk_fma_f32 v[6:7], v[36:37], v[2:3], v[6:7]
	v_add_f32_dpp v0, v0, v0 quad_perm:[1,0,3,2] row_mask:0xf bank_mask:0xf bound_ctrl:1
	v_pk_mul_f32 v[10:11], v[46:47], v[14:15] op_sel_hi:[1,0]
	v_pk_mul_f32 v[8:9], v[44:45], v[14:15] op_sel_hi:[1,0]
	v_add_f32_dpp v0, v0, v0 quad_perm:[2,3,0,1] row_mask:0xf bank_mask:0xf bound_ctrl:1
	ds_read_b128 v[24:27], v83 offset:27648
	ds_read_b128 v[28:31], v83 offset:3072
	ds_read_b128 v[32:35], v83 offset:19456
	ds_read_b128 v[36:39], v83 offset:35840
	ds_read_b128 v[40:43], v83 offset:11520
	v_add_f32_e32 v87, v6, v7
	ds_write2st64_b32 v85, v86, v87 offset0:32 offset1:36
	v_add_f32_dpp v0, v0, v0 row_half_mirror row_mask:0xf bank_mask:0xf bound_ctrl:1
	v_pk_fma_f32 v[10:11], v[50:51], v[4:5], v[10:11]
	v_pk_fma_f32 v[8:9], v[48:49], v[2:3], v[8:9]
	v_add_f32_dpp v0, v0, v0 row_mirror row_mask:0xf bank_mask:0xf bound_ctrl:1
	v_pk_fma_f32 v[4:5], v[54:55], v[0:1], v[10:11] op_sel_hi:[1,0,1]
	v_pk_mul_f32 v[6:7], v[62:63], v[4:5]
	v_pk_fma_f32 v[2:3], v[52:53], v[0:1], v[8:9] op_sel_hi:[1,0,1]
	v_pk_fma_f32 v[6:7], v[60:61], v[2:3], v[6:7]
	s_waitcnt lgkmcnt(7)
	v_add_f32_e32 v0, v6, v7
	v_pk_mul_f32 v[6:7], v[58:59], v[4:5]
	v_pk_fma_f32 v[6:7], v[56:57], v[2:3], v[6:7]
	v_add_f32_dpp v0, v0, v0 quad_perm:[1,0,3,2] row_mask:0xf bank_mask:0xf bound_ctrl:1
	v_pk_mul_f32 v[10:11], v[66:67], v[14:15] op_sel:[0,1] op_sel_hi:[1,1]
	v_pk_mul_f32 v[8:9], v[64:65], v[14:15] op_sel:[0,1] op_sel_hi:[1,1]
	v_add_f32_dpp v0, v0, v0 quad_perm:[2,3,0,1] row_mask:0xf bank_mask:0xf bound_ctrl:1
	ds_read_b128 v[44:47], v83 offset:27904
	ds_read_b128 v[48:51], v83 offset:3328
	ds_read_b128 v[52:55], v83 offset:19712
	ds_read_b128 v[56:59], v83 offset:36096
	ds_read_b128 v[60:63], v83 offset:11776
	v_add_f32_e32 v86, v6, v7
	v_add_f32_dpp v0, v0, v0 row_half_mirror row_mask:0xf bank_mask:0xf bound_ctrl:1
	v_pk_fma_f32 v[10:11], v[70:71], v[4:5], v[10:11]
	v_pk_fma_f32 v[8:9], v[68:69], v[2:3], v[8:9]
	v_add_f32_dpp v0, v0, v0 row_mirror row_mask:0xf bank_mask:0xf bound_ctrl:1
	v_pk_fma_f32 v[4:5], v[74:75], v[0:1], v[10:11] op_sel_hi:[1,0,1]
	v_pk_mul_f32 v[6:7], v[22:23], v[4:5]
	v_pk_fma_f32 v[2:3], v[72:73], v[0:1], v[8:9] op_sel_hi:[1,0,1]
	v_pk_fma_f32 v[6:7], v[20:21], v[2:3], v[6:7]
	s_waitcnt lgkmcnt(6)
; #define LAS __attribute__((address_space(3)))
; __device__ __forceinline__ void phase_rwc(const int wvs, const Params& p, LAS unsigned char* lds, int layer, int wg0) {
;     ...
;       for (int t = 0; t < 32; ++t) {
;         const int tn = t + 2;
;         const f32x4 nw4 = *(const LAS f32x4*)(Wv + tn * 64), nkk4 = *(const LAS f32x4*)(Wv + 2048 + tn * 64), nb4 = *(const LAS f32x4*)(Wv + 4096 + tn * 64), nkd4 = *(const LAS f32x4*)(Wv + 6144 + tn * 64), nr4 = *(const LAS f32x4*)(Wv + 8192 + tn * 64);
;         const float nvv = Vv[tn * 16];
;         const f32x4 pa = S * kk4;
;         const f32x4 t1 = S * w4 + vv * kd4;
;         float sa = (pa[0] + pa[2]) + (pa[1] + pa[3]);
;         sa = row16_sum(sa);
;         S = t1 + sa * b4;
;         const f32x4 py = S * r4;
;         ypw[t * 256] = (py[0] + py[2]) + (py[1] + py[3]);
;         w4 = xw4; kk4 = xkk4; b4 = xb4; kd4 = xkd4; r4 = xr4; vv = xvv;
;         xw4 = nw4; xkk4 = nkk4; xb4 = nb4; xkd4 = nkd4; xr4 = nr4; xvv = nvv;
;       }
	v_add_f32_e32 v0, v6, v7
	v_pk_mul_f32 v[6:7], v[78:79], v[4:5]
	v_pk_fma_f32 v[6:7], v[76:77], v[2:3], v[6:7]
	v_add_f32_dpp v0, v0, v0 quad_perm:[1,0,3,2] row_mask:0xf bank_mask:0xf bound_ctrl:1
	v_pk_mul_f32 v[10:11], v[26:27], v[16:17] op_sel_hi:[1,0]
	v_pk_mul_f32 v[8:9], v[24:25], v[16:17] op_sel_hi:[1,0]
	v_add_f32_dpp v0, v0, v0 quad_perm:[2,3,0,1] row_mask:0xf bank_mask:0xf bound_ctrl:1
	ds_read_b128 v[64:67], v83 offset:28160
	ds_read_b128 v[68:71], v83 offset:3584
	ds_read_b128 v[72:75], v83 offset:19968
	ds_read_b128 v[76:79], v83 offset:36352
	ds_read_b128 v[20:23], v83 offset:12032
	v_add_f32_e32 v87, v6, v7
	ds_write2st64_b32 v85, v86, v87 offset0:40 offset1:44
	v_add_f32_dpp v0, v0, v0 row_half_mirror row_mask:0xf bank_mask:0xf bound_ctrl:1
	v_pk_fma_f32 v[10:11], v[30:31], v[4:5], v[10:11]
	v_pk_fma_f32 v[8:9], v[28:29], v[2:3], v[8:9]
	v_add_f32_dpp v0, v0, v0 row_mirror row_mask:0xf bank_mask:0xf bound_ctrl:1
	v_pk_fma_f32 v[4:5], v[34:35], v[0:1], v[10:11] op_sel_hi:[1,0,1]
	v_pk_mul_f32 v[6:7], v[42:43], v[4:5]
	v_pk_fma_f32 v[2:3], v[32:33], v[0:1], v[8:9] op_sel_hi:[1,0,1]
	v_pk_fma_f32 v[6:7], v[40:41], v[2:3], v[6:7]
	s_waitcnt lgkmcnt(6)
	v_add_f32_e32 v0, v6, v7
	v_pk_mul_f32 v[6:7], v[38:39], v[4:5]
	v_pk_fma_f32 v[6:7], v[36:37], v[2:3], v[6:7]
	v_add_f32_dpp v0, v0, v0 quad_perm:[1,0,3,2] row_mask:0xf bank_mask:0xf bound_ctrl:1
	v_pk_mul_f32 v[10:11], v[46:47], v[16:17] op_sel:[0,1] op_sel_hi:[1,1]
	v_pk_mul_f32 v[8:9], v[44:45], v[16:17] op_sel:[0,1] op_sel_hi:[1,1]
	v_add_f32_dpp v0, v0, v0 quad_perm:[2,3,0,1] row_mask:0xf bank_mask:0xf bound_ctrl:1
	ds_read_b128 v[24:27], v83 offset:28416
	ds_read_b128 v[28:31], v83 offset:3840
	ds_read_b128 v[32:35], v83 offset:20224
	ds_read_b128 v[36:39], v83 offset:36608
	ds_read_b128 v[40:43], v83 offset:12288
	ds_read_b128 v[12:15], v84 offset:64
	v_add_f32_e32 v86, v6, v7
	v_add_f32_dpp v0, v0, v0 row_half_mirror row_mask:0xf bank_mask:0xf bound_ctrl:1
	v_pk_fma_f32 v[10:11], v[50:51], v[4:5], v[10:11]
	v_pk_fma_f32 v[8:9], v[48:49], v[2:3], v[8:9]
	v_add_f32_dpp v0, v0, v0 row_mirror row_mask:0xf bank_mask:0xf bound_ctrl:1
	v_pk_fma_f32 v[4:5], v[54:55], v[0:1], v[10:11] op_sel_hi:[1,0,1]
	v_pk_mul_f32 v[6:7], v[62:63], v[4:5]
	v_pk_fma_f32 v[2:3], v[52:53], v[0:1], v[8:9] op_sel_hi:[1,0,1]
	v_pk_fma_f32 v[6:7], v[60:61], v[2:3], v[6:7]
	s_waitcnt lgkmcnt(7)
	v_add_f32_e32 v0, v6, v7
	v_pk_mul_f32 v[6:7], v[58:59], v[4:5]
	v_pk_fma_f32 v[6:7], v[56:57], v[2:3], v[6:7]
	v_add_f32_dpp v0, v0, v0 quad_perm:[1,0,3,2] row_mask:0xf bank_mask:0xf bound_ctrl:1
	v_pk_mul_f32 v[10:11], v[66:67], v[18:19] op_sel_hi:[1,0]
	v_pk_mul_f32 v[8:9], v[64:65], v[18:19] op_sel_hi:[1,0]
	v_add_f32_dpp v0, v0, v0 quad_perm:[2,3,0,1] row_mask:0xf bank_mask:0xf bound_ctrl:1
	ds_read_b128 v[44:47], v83 offset:28672
	ds_read_b128 v[48:51], v83 offset:4096
	ds_read_b128 v[52:55], v83 offset:20480
	ds_read_b128 v[56:59], v83 offset:36864
	ds_read_b128 v[60:63], v83 offset:12544
	v_add_f32_e32 v87, v6, v7
	ds_write2st64_b32 v85, v86, v87 offset0:48 offset1:52
	v_add_f32_dpp v0, v0, v0 row_half_mirror row_mask:0xf bank_mask:0xf bound_ctrl:1
	v_pk_fma_f32 v[10:11], v[70:71], v[4:5], v[10:11]
	v_pk_fma_f32 v[8:9], v[68:69], v[2:3], v[8:9]
	v_add_f32_dpp v0, v0, v0 row_mirror row_mask:0xf bank_mask:0xf bound_ctrl:1
	v_pk_fma_f32 v[4:5], v[74:75], v[0:1], v[10:11] op_sel_hi:[1,0,1]
	v_pk_mul_f32 v[6:7], v[22:23], v[4:5]
	v_pk_fma_f32 v[2:3], v[72:73], v[0:1], v[8:9] op_sel_hi:[1,0,1]
	v_pk_fma_f32 v[6:7], v[20:21], v[2:3], v[6:7]
	s_waitcnt lgkmcnt(7)
	v_add_f32_e32 v0, v6, v7
	v_pk_mul_f32 v[6:7], v[78:79], v[4:5]
	v_pk_fma_f32 v[6:7], v[76:77], v[2:3], v[6:7]
	v_add_f32_dpp v0, v0, v0 quad_perm:[1,0,3,2] row_mask:0xf bank_mask:0xf bound_ctrl:1
	v_pk_mul_f32 v[10:11], v[26:27], v[18:19] op_sel:[0,1] op_sel_hi:[1,1]
	v_pk_mul_f32 v[8:9], v[24:25], v[18:19] op_sel:[0,1] op_sel_hi:[1,1]
	v_add_f32_dpp v0, v0, v0 quad_perm:[2,3,0,1] row_mask:0xf bank_mask:0xf bound_ctrl:1
	ds_read_b128 v[64:67], v83 offset:28928
	ds_read_b128 v[68:71], v83 offset:4352
	ds_read_b128 v[72:75], v83 offset:20736
	ds_read_b128 v[76:79], v83 offset:37120
	ds_read_b128 v[20:23], v83 offset:12800
	v_add_f32_e32 v86, v6, v7
	v_add_f32_dpp v0, v0, v0 row_half_mirror row_mask:0xf bank_mask:0xf bound_ctrl:1
	v_pk_fma_f32 v[10:11], v[30:31], v[4:5], v[10:11]
	v_pk_fma_f32 v[8:9], v[28:29], v[2:3], v[8:9]
	v_add_f32_dpp v0, v0, v0 row_mirror row_mask:0xf bank_mask:0xf bound_ctrl:1
	v_pk_fma_f32 v[4:5], v[34:35], v[0:1], v[10:11] op_sel_hi:[1,0,1]
	v_pk_mul_f32 v[6:7], v[42:43], v[4:5]
	v_pk_fma_f32 v[2:3], v[32:33], v[0:1], v[8:9] op_sel_hi:[1,0,1]
	v_pk_fma_f32 v[6:7], v[40:41], v[2:3], v[6:7]
	s_waitcnt lgkmcnt(6)
	v_add_f32_e32 v0, v6, v7
	v_pk_mul_f32 v[6:7], v[38:39], v[4:5]
	v_pk_fma_f32 v[6:7], v[36:37], v[2:3], v[6:7]
	v_add_f32_dpp v0, v0, v0 quad_perm:[1,0,3,2] row_mask:0xf bank_mask:0xf bound_ctrl:1
	v_pk_mul_f32 v[10:11], v[46:47], v[12:13] op_sel_hi:[1,0]
	v_pk_mul_f32 v[8:9], v[44:45], v[12:13] op_sel_hi:[1,0]
	v_add_f32_dpp v0, v0, v0 quad_perm:[2,3,0,1] row_mask:0xf bank_mask:0xf bound_ctrl:1
	ds_read_b128 v[24:27], v83 offset:29184
	ds_read_b128 v[28:31], v83 offset:4608
	ds_read_b128 v[32:35], v83 offset:20992
	ds_read_b128 v[36:39], v83 offset:37376
	ds_read_b128 v[40:43], v83 offset:13056
	v_add_f32_e32 v87, v6, v7
	ds_write2st64_b32 v85, v86, v87 offset0:56 offset1:60
	v_add_f32_dpp v0, v0, v0 row_half_mirror row_mask:0xf bank_mask:0xf bound_ctrl:1
	v_pk_fma_f32 v[10:11], v[50:51], v[4:5], v[10:11]
	v_pk_fma_f32 v[8:9], v[48:49], v[2:3], v[8:9]
	v_add_f32_dpp v0, v0, v0 row_mirror row_mask:0xf bank_mask:0xf bound_ctrl:1
	v_pk_fma_f32 v[4:5], v[54:55], v[0:1], v[10:11] op_sel_hi:[1,0,1]
	v_pk_mul_f32 v[6:7], v[62:63], v[4:5]
	v_pk_fma_f32 v[2:3], v[52:53], v[0:1], v[8:9] op_sel_hi:[1,0,1]
	v_pk_fma_f32 v[6:7], v[60:61], v[2:3], v[6:7]
	s_waitcnt lgkmcnt(6)
; #define LAS __attribute__((address_space(3)))
; __device__ __forceinline__ void phase_rwc(const int wvs, const Params& p, LAS unsigned char* lds, int layer, int wg0) {
;     ...
;       for (int t = 0; t < 32; ++t) {
;         const int tn = t + 2;
;         const f32x4 nw4 = *(const LAS f32x4*)(Wv + tn * 64), nkk4 = *(const LAS f32x4*)(Wv + 2048 + tn * 64), nb4 = *(const LAS f32x4*)(Wv + 4096 + tn * 64), nkd4 = *(const LAS f32x4*)(Wv + 6144 + tn * 64), nr4 = *(const LAS f32x4*)(Wv + 8192 + tn * 64);
;         const float nvv = Vv[tn * 16];
;         const f32x4 pa = S * kk4;
;         const f32x4 t1 = S * w4 + vv * kd4;
;         float sa = (pa[0] + pa[2]) + (pa[1] + pa[3]);
;         sa = row16_sum(sa);
;         S = t1 + sa * b4;
;         const f32x4 py = S * r4;
;         ypw[t * 256] = (py[0] + py[2]) + (py[1] + py[3]);
;         w4 = xw4; kk4 = xkk4; b4 = xb4; kd4 = xkd4; r4 = xr4; vv = xvv;
;         xw4 = nw4; xkk4 = nkk4; xb4 = nb4; xkd4 = nkd4; xr4 = nr4; xvv = nvv;
;       }
	v_add_f32_e32 v0, v6, v7
	v_pk_mul_f32 v[6:7], v[58:59], v[4:5]
	v_pk_fma_f32 v[6:7], v[56:57], v[2:3], v[6:7]
	v_add_f32_dpp v0, v0, v0 quad_perm:[1,0,3,2] row_mask:0xf bank_mask:0xf bound_ctrl:1
	v_pk_mul_f32 v[10:11], v[66:67], v[12:13] op_sel:[0,1] op_sel_hi:[1,1]
	v_pk_mul_f32 v[8:9], v[64:65], v[12:13] op_sel:[0,1] op_sel_hi:[1,1]
	v_add_f32_dpp v0, v0, v0 quad_perm:[2,3,0,1] row_mask:0xf bank_mask:0xf bound_ctrl:1
	ds_read_b128 v[44:47], v83 offset:29440
	ds_read_b128 v[48:51], v83 offset:4864
	ds_read_b128 v[52:55], v83 offset:21248
	ds_read_b128 v[56:59], v83 offset:37632
	ds_read_b128 v[60:63], v83 offset:13312
	ds_read_b128 v[16:19], v84 offset:80
	v_add_f32_e32 v86, v6, v7
	v_add_f32_dpp v0, v0, v0 row_half_mirror row_mask:0xf bank_mask:0xf bound_ctrl:1
	v_pk_fma_f32 v[10:11], v[70:71], v[4:5], v[10:11]
	v_pk_fma_f32 v[8:9], v[68:69], v[2:3], v[8:9]
	v_add_f32_dpp v0, v0, v0 row_mirror row_mask:0xf bank_mask:0xf bound_ctrl:1
	v_pk_fma_f32 v[4:5], v[74:75], v[0:1], v[10:11] op_sel_hi:[1,0,1]
	v_pk_mul_f32 v[6:7], v[22:23], v[4:5]
	v_pk_fma_f32 v[2:3], v[72:73], v[0:1], v[8:9] op_sel_hi:[1,0,1]
	v_pk_fma_f32 v[6:7], v[20:21], v[2:3], v[6:7]
	s_waitcnt lgkmcnt(7)
	v_add_f32_e32 v0, v6, v7
	v_pk_mul_f32 v[6:7], v[78:79], v[4:5]
	v_pk_fma_f32 v[6:7], v[76:77], v[2:3], v[6:7]
	v_add_f32_dpp v0, v0, v0 quad_perm:[1,0,3,2] row_mask:0xf bank_mask:0xf bound_ctrl:1
	v_pk_mul_f32 v[10:11], v[26:27], v[14:15] op_sel_hi:[1,0]
	v_pk_mul_f32 v[8:9], v[24:25], v[14:15] op_sel_hi:[1,0]
	v_add_f32_dpp v0, v0, v0 quad_perm:[2,3,0,1] row_mask:0xf bank_mask:0xf bound_ctrl:1
	ds_read_b128 v[64:67], v83 offset:29696
	ds_read_b128 v[68:71], v83 offset:5120
	ds_read_b128 v[72:75], v83 offset:21504
	ds_read_b128 v[76:79], v83 offset:37888
	ds_read_b128 v[20:23], v83 offset:13568
	v_add_f32_e32 v87, v6, v7
	ds_write2st64_b32 v85, v86, v87 offset0:64 offset1:68
	v_add_f32_dpp v0, v0, v0 row_half_mirror row_mask:0xf bank_mask:0xf bound_ctrl:1
	v_pk_fma_f32 v[10:11], v[30:31], v[4:5], v[10:11]
	v_pk_fma_f32 v[8:9], v[28:29], v[2:3], v[8:9]
	v_add_f32_dpp v0, v0, v0 row_mirror row_mask:0xf bank_mask:0xf bound_ctrl:1
	v_pk_fma_f32 v[4:5], v[34:35], v[0:1], v[10:11] op_sel_hi:[1,0,1]
	v_pk_mul_f32 v[6:7], v[42:43], v[4:5]
	v_pk_fma_f32 v[2:3], v[32:33], v[0:1], v[8:9] op_sel_hi:[1,0,1]
	v_pk_fma_f32 v[6:7], v[40:41], v[2:3], v[6:7]
	s_waitcnt lgkmcnt(7)
	v_add_f32_e32 v0, v6, v7
	v_pk_mul_f32 v[6:7], v[38:39], v[4:5]
	v_pk_fma_f32 v[6:7], v[36:37], v[2:3], v[6:7]
	v_add_f32_dpp v0, v0, v0 quad_perm:[1,0,3,2] row_mask:0xf bank_mask:0xf bound_ctrl:1
	v_pk_mul_f32 v[10:11], v[46:47], v[14:15] op_sel:[0,1] op_sel_hi:[1,1]
	v_pk_mul_f32 v[8:9], v[44:45], v[14:15] op_sel:[0,1] op_sel_hi:[1,1]
	v_add_f32_dpp v0, v0, v0 quad_perm:[2,3,0,1] row_mask:0xf bank_mask:0xf bound_ctrl:1
	ds_read_b128 v[24:27], v83 offset:29952
	ds_read_b128 v[28:31], v83 offset:5376
	ds_read_b128 v[32:35], v83 offset:21760
	ds_read_b128 v[36:39], v83 offset:38144
	ds_read_b128 v[40:43], v83 offset:13824
	v_add_f32_e32 v86, v6, v7
	v_add_f32_dpp v0, v0, v0 row_half_mirror row_mask:0xf bank_mask:0xf bound_ctrl:1
	v_pk_fma_f32 v[10:11], v[50:51], v[4:5], v[10:11]
	v_pk_fma_f32 v[8:9], v[48:49], v[2:3], v[8:9]
	v_add_f32_dpp v0, v0, v0 row_mirror row_mask:0xf bank_mask:0xf bound_ctrl:1
	v_pk_fma_f32 v[4:5], v[54:55], v[0:1], v[10:11] op_sel_hi:[1,0,1]
	v_pk_mul_f32 v[6:7], v[62:63], v[4:5]
	v_pk_fma_f32 v[2:3], v[52:53], v[0:1], v[8:9] op_sel_hi:[1,0,1]
	v_pk_fma_f32 v[6:7], v[60:61], v[2:3], v[6:7]
	s_waitcnt lgkmcnt(6)
	v_add_f32_e32 v0, v6, v7
	v_pk_mul_f32 v[6:7], v[58:59], v[4:5]
	v_pk_fma_f32 v[6:7], v[56:57], v[2:3], v[6:7]
	v_add_f32_dpp v0, v0, v0 quad_perm:[1,0,3,2] row_mask:0xf bank_mask:0xf bound_ctrl:1
	v_pk_mul_f32 v[10:11], v[66:67], v[16:17] op_sel_hi:[1,0]
	v_pk_mul_f32 v[8:9], v[64:65], v[16:17] op_sel_hi:[1,0]
	v_add_f32_dpp v0, v0, v0 quad_perm:[2,3,0,1] row_mask:0xf bank_mask:0xf bound_ctrl:1
	ds_read_b128 v[44:47], v83 offset:30208
	ds_read_b128 v[48:51], v83 offset:5632
	ds_read_b128 v[52:55], v83 offset:22016
	ds_read_b128 v[56:59], v83 offset:38400
	ds_read_b128 v[60:63], v83 offset:14080
	v_add_f32_e32 v87, v6, v7
	ds_write2st64_b32 v85, v86, v87 offset0:72 offset1:76
	v_add_f32_dpp v0, v0, v0 row_half_mirror row_mask:0xf bank_mask:0xf bound_ctrl:1
	v_pk_fma_f32 v[10:11], v[70:71], v[4:5], v[10:11]
	v_pk_fma_f32 v[8:9], v[68:69], v[2:3], v[8:9]
	v_add_f32_dpp v0, v0, v0 row_mirror row_mask:0xf bank_mask:0xf bound_ctrl:1
	v_pk_fma_f32 v[4:5], v[74:75], v[0:1], v[10:11] op_sel_hi:[1,0,1]
	v_pk_mul_f32 v[6:7], v[22:23], v[4:5]
	v_pk_fma_f32 v[2:3], v[72:73], v[0:1], v[8:9] op_sel_hi:[1,0,1]
	v_pk_fma_f32 v[6:7], v[20:21], v[2:3], v[6:7]
	s_waitcnt lgkmcnt(6)
	v_add_f32_e32 v0, v6, v7
	v_pk_mul_f32 v[6:7], v[78:79], v[4:5]
	v_pk_fma_f32 v[6:7], v[76:77], v[2:3], v[6:7]
	v_add_f32_dpp v0, v0, v0 quad_perm:[1,0,3,2] row_mask:0xf bank_mask:0xf bound_ctrl:1
	v_pk_mul_f32 v[10:11], v[26:27], v[16:17] op_sel:[0,1] op_sel_hi:[1,1]
	v_pk_mul_f32 v[8:9], v[24:25], v[16:17] op_sel:[0,1] op_sel_hi:[1,1]
	v_add_f32_dpp v0, v0, v0 quad_perm:[2,3,0,1] row_mask:0xf bank_mask:0xf bound_ctrl:1
	ds_read_b128 v[64:67], v83 offset:30464
	ds_read_b128 v[68:71], v83 offset:5888
	ds_read_b128 v[72:75], v83 offset:22272
	ds_read_b128 v[76:79], v83 offset:38656
	ds_read_b128 v[20:23], v83 offset:14336
	ds_read_b128 v[12:15], v84 offset:96
	v_add_f32_e32 v86, v6, v7
	v_add_f32_dpp v0, v0, v0 row_half_mirror row_mask:0xf bank_mask:0xf bound_ctrl:1
	v_pk_fma_f32 v[10:11], v[30:31], v[4:5], v[10:11]
	v_pk_fma_f32 v[8:9], v[28:29], v[2:3], v[8:9]
	v_add_f32_dpp v0, v0, v0 row_mirror row_mask:0xf bank_mask:0xf bound_ctrl:1
	v_pk_fma_f32 v[4:5], v[34:35], v[0:1], v[10:11] op_sel_hi:[1,0,1]
	v_pk_mul_f32 v[6:7], v[42:43], v[4:5]
	v_pk_fma_f32 v[2:3], v[32:33], v[0:1], v[8:9] op_sel_hi:[1,0,1]
	v_pk_fma_f32 v[6:7], v[40:41], v[2:3], v[6:7]
	s_waitcnt lgkmcnt(7)
; #define LAS __attribute__((address_space(3)))
; __device__ __forceinline__ void phase_rwc(const int wvs, const Params& p, LAS unsigned char* lds, int layer, int wg0) {
;     ...
;       for (int t = 0; t < 32; ++t) {
;         const int tn = t + 2;
;         const f32x4 nw4 = *(const LAS f32x4*)(Wv + tn * 64), nkk4 = *(const LAS f32x4*)(Wv + 2048 + tn * 64), nb4 = *(const LAS f32x4*)(Wv + 4096 + tn * 64), nkd4 = *(const LAS f32x4*)(Wv + 6144 + tn * 64), nr4 = *(const LAS f32x4*)(Wv + 8192 + tn * 64);
;         const float nvv = Vv[tn * 16];
;         const f32x4 pa = S * kk4;
;         const f32x4 t1 = S * w4 + vv * kd4;
;         float sa = (pa[0] + pa[2]) + (pa[1] + pa[3]);
;         sa = row16_sum(sa);
;         S = t1 + sa * b4;
;         const f32x4 py = S * r4;
;         ypw[t * 256] = (py[0] + py[2]) + (py[1] + py[3]);
;         w4 = xw4; kk4 = xkk4; b4 = xb4; kd4 = xkd4; r4 = xr4; vv = xvv;
;         xw4 = nw4; xkk4 = nkk4; xb4 = nb4; xkd4 = nkd4; xr4 = nr4; xvv = nvv;
;       }
	v_add_f32_e32 v0, v6, v7
	v_pk_mul_f32 v[6:7], v[38:39], v[4:5]
	v_pk_fma_f32 v[6:7], v[36:37], v[2:3], v[6:7]
	v_add_f32_dpp v0, v0, v0 quad_perm:[1,0,3,2] row_mask:0xf bank_mask:0xf bound_ctrl:1
	v_pk_mul_f32 v[10:11], v[46:47], v[18:19] op_sel_hi:[1,0]
	v_pk_mul_f32 v[8:9], v[44:45], v[18:19] op_sel_hi:[1,0]
	v_add_f32_dpp v0, v0, v0 quad_perm:[2,3,0,1] row_mask:0xf bank_mask:0xf bound_ctrl:1
	ds_read_b128 v[24:27], v83 offset:30720
	ds_read_b128 v[28:31], v83 offset:6144
	ds_read_b128 v[32:35], v83 offset:22528
	ds_read_b128 v[36:39], v83 offset:38912
	ds_read_b128 v[40:43], v83 offset:14592
	v_add_f32_e32 v87, v6, v7
	ds_write2st64_b32 v85, v86, v87 offset0:80 offset1:84
	v_add_f32_dpp v0, v0, v0 row_half_mirror row_mask:0xf bank_mask:0xf bound_ctrl:1
	v_pk_fma_f32 v[10:11], v[50:51], v[4:5], v[10:11]
	v_pk_fma_f32 v[8:9], v[48:49], v[2:3], v[8:9]
	v_add_f32_dpp v0, v0, v0 row_mirror row_mask:0xf bank_mask:0xf bound_ctrl:1
	v_pk_fma_f32 v[4:5], v[54:55], v[0:1], v[10:11] op_sel_hi:[1,0,1]
	v_pk_mul_f32 v[6:7], v[62:63], v[4:5]
	v_pk_fma_f32 v[2:3], v[52:53], v[0:1], v[8:9] op_sel_hi:[1,0,1]
	v_pk_fma_f32 v[6:7], v[60:61], v[2:3], v[6:7]
	s_waitcnt lgkmcnt(7)
	v_add_f32_e32 v0, v6, v7
	v_pk_mul_f32 v[6:7], v[58:59], v[4:5]
	v_pk_fma_f32 v[6:7], v[56:57], v[2:3], v[6:7]
	v_add_f32_dpp v0, v0, v0 quad_perm:[1,0,3,2] row_mask:0xf bank_mask:0xf bound_ctrl:1
	v_pk_mul_f32 v[10:11], v[66:67], v[18:19] op_sel:[0,1] op_sel_hi:[1,1]
	v_pk_mul_f32 v[8:9], v[64:65], v[18:19] op_sel:[0,1] op_sel_hi:[1,1]
	v_add_f32_dpp v0, v0, v0 quad_perm:[2,3,0,1] row_mask:0xf bank_mask:0xf bound_ctrl:1
	ds_read_b128 v[44:47], v83 offset:30976
	ds_read_b128 v[48:51], v83 offset:6400
	ds_read_b128 v[52:55], v83 offset:22784
	ds_read_b128 v[56:59], v83 offset:39168
	ds_read_b128 v[60:63], v83 offset:14848
	v_add_f32_e32 v86, v6, v7
	v_add_f32_dpp v0, v0, v0 row_half_mirror row_mask:0xf bank_mask:0xf bound_ctrl:1
	v_pk_fma_f32 v[10:11], v[70:71], v[4:5], v[10:11]
	v_pk_fma_f32 v[8:9], v[68:69], v[2:3], v[8:9]
	v_add_f32_dpp v0, v0, v0 row_mirror row_mask:0xf bank_mask:0xf bound_ctrl:1
	v_pk_fma_f32 v[4:5], v[74:75], v[0:1], v[10:11] op_sel_hi:[1,0,1]
	v_pk_mul_f32 v[6:7], v[22:23], v[4:5]
	v_pk_fma_f32 v[2:3], v[72:73], v[0:1], v[8:9] op_sel_hi:[1,0,1]
	v_pk_fma_f32 v[6:7], v[20:21], v[2:3], v[6:7]
	s_waitcnt lgkmcnt(6)
	v_add_f32_e32 v0, v6, v7
	v_pk_mul_f32 v[6:7], v[78:79], v[4:5]
	v_pk_fma_f32 v[6:7], v[76:77], v[2:3], v[6:7]
	v_add_f32_dpp v0, v0, v0 quad_perm:[1,0,3,2] row_mask:0xf bank_mask:0xf bound_ctrl:1
	v_pk_mul_f32 v[10:11], v[26:27], v[12:13] op_sel_hi:[1,0]
	v_pk_mul_f32 v[8:9], v[24:25], v[12:13] op_sel_hi:[1,0]
	v_add_f32_dpp v0, v0, v0 quad_perm:[2,3,0,1] row_mask:0xf bank_mask:0xf bound_ctrl:1
	ds_read_b128 v[64:67], v83 offset:31232
	ds_read_b128 v[68:71], v83 offset:6656
	ds_read_b128 v[72:75], v83 offset:23040
	ds_read_b128 v[76:79], v83 offset:39424
	ds_read_b128 v[20:23], v83 offset:15104
	v_add_f32_e32 v87, v6, v7
	ds_write2st64_b32 v85, v86, v87 offset0:88 offset1:92
	v_add_f32_dpp v0, v0, v0 row_half_mirror row_mask:0xf bank_mask:0xf bound_ctrl:1
	v_pk_fma_f32 v[10:11], v[30:31], v[4:5], v[10:11]
	v_pk_fma_f32 v[8:9], v[28:29], v[2:3], v[8:9]
	v_add_f32_dpp v0, v0, v0 row_mirror row_mask:0xf bank_mask:0xf bound_ctrl:1
	v_pk_fma_f32 v[4:5], v[34:35], v[0:1], v[10:11] op_sel_hi:[1,0,1]
	v_pk_mul_f32 v[6:7], v[42:43], v[4:5]
	v_pk_fma_f32 v[2:3], v[32:33], v[0:1], v[8:9] op_sel_hi:[1,0,1]
	v_pk_fma_f32 v[6:7], v[40:41], v[2:3], v[6:7]
	s_waitcnt lgkmcnt(6)
	v_add_f32_e32 v0, v6, v7
	v_pk_mul_f32 v[6:7], v[38:39], v[4:5]
	v_pk_fma_f32 v[6:7], v[36:37], v[2:3], v[6:7]
	v_add_f32_dpp v0, v0, v0 quad_perm:[1,0,3,2] row_mask:0xf bank_mask:0xf bound_ctrl:1
	v_pk_mul_f32 v[10:11], v[46:47], v[12:13] op_sel:[0,1] op_sel_hi:[1,1]
	v_pk_mul_f32 v[8:9], v[44:45], v[12:13] op_sel:[0,1] op_sel_hi:[1,1]
	v_add_f32_dpp v0, v0, v0 quad_perm:[2,3,0,1] row_mask:0xf bank_mask:0xf bound_ctrl:1
	ds_read_b128 v[24:27], v83 offset:31488
	ds_read_b128 v[28:31], v83 offset:6912
	ds_read_b128 v[32:35], v83 offset:23296
	ds_read_b128 v[36:39], v83 offset:39680
	ds_read_b128 v[40:43], v83 offset:15360
	ds_read_b128 v[16:19], v84 offset:112
	v_add_f32_e32 v86, v6, v7
	v_add_f32_dpp v0, v0, v0 row_half_mirror row_mask:0xf bank_mask:0xf bound_ctrl:1
	v_pk_fma_f32 v[10:11], v[50:51], v[4:5], v[10:11]
	v_pk_fma_f32 v[8:9], v[48:49], v[2:3], v[8:9]
	v_add_f32_dpp v0, v0, v0 row_mirror row_mask:0xf bank_mask:0xf bound_ctrl:1
	v_pk_fma_f32 v[4:5], v[54:55], v[0:1], v[10:11] op_sel_hi:[1,0,1]
	v_pk_mul_f32 v[6:7], v[62:63], v[4:5]
	v_pk_fma_f32 v[2:3], v[52:53], v[0:1], v[8:9] op_sel_hi:[1,0,1]
	v_pk_fma_f32 v[6:7], v[60:61], v[2:3], v[6:7]
	s_waitcnt lgkmcnt(7)
	v_add_f32_e32 v0, v6, v7
	v_pk_mul_f32 v[6:7], v[58:59], v[4:5]
	v_pk_fma_f32 v[6:7], v[56:57], v[2:3], v[6:7]
	v_add_f32_dpp v0, v0, v0 quad_perm:[1,0,3,2] row_mask:0xf bank_mask:0xf bound_ctrl:1
	v_pk_mul_f32 v[10:11], v[66:67], v[14:15] op_sel_hi:[1,0]
	v_pk_mul_f32 v[8:9], v[64:65], v[14:15] op_sel_hi:[1,0]
	v_add_f32_dpp v0, v0, v0 quad_perm:[2,3,0,1] row_mask:0xf bank_mask:0xf bound_ctrl:1
	ds_read_b128 v[44:47], v83 offset:31744
	ds_read_b128 v[48:51], v83 offset:7168
	ds_read_b128 v[52:55], v83 offset:23552
	ds_read_b128 v[56:59], v83 offset:39936
	ds_read_b128 v[60:63], v83 offset:15616
	v_add_f32_e32 v87, v6, v7
	ds_write2st64_b32 v85, v86, v87 offset0:96 offset1:100
	v_add_f32_dpp v0, v0, v0 row_half_mirror row_mask:0xf bank_mask:0xf bound_ctrl:1
	v_pk_fma_f32 v[10:11], v[70:71], v[4:5], v[10:11]
	v_pk_fma_f32 v[8:9], v[68:69], v[2:3], v[8:9]
	v_add_f32_dpp v0, v0, v0 row_mirror row_mask:0xf bank_mask:0xf bound_ctrl:1
	v_pk_fma_f32 v[4:5], v[74:75], v[0:1], v[10:11] op_sel_hi:[1,0,1]
	v_pk_mul_f32 v[6:7], v[22:23], v[4:5]
	v_pk_fma_f32 v[2:3], v[72:73], v[0:1], v[8:9] op_sel_hi:[1,0,1]
	v_pk_fma_f32 v[6:7], v[20:21], v[2:3], v[6:7]
	s_waitcnt lgkmcnt(7)
; #define LAS __attribute__((address_space(3)))
; __device__ __forceinline__ void phase_rwc(const int wvs, const Params& p, LAS unsigned char* lds, int layer, int wg0) {
;     ...
; #pragma unroll 2
;     for (int blk = 0; blk < NBLK; ++blk) {
;       LAS float* Wv = (LAS float*)(lds + (blk & 1) * BUFSZ) + kg * 4; LAS float* Vv = (LAS float*)(lds + (blk & 1) * BUFSZ) + 5 * 2048 + rowl;
;       LAS float* ypw = (LAS float*)(lds + YOFF + (blk & 1) * YSZ) + rowl * 16 + kg;
;       asm volatile("" : "+v"(Wv), "+v"(Vv), "+v"(ypw));
;       f32x4 w4 = *(const LAS f32x4*)(Wv), kk4 = *(const LAS f32x4*)(Wv + 2048), b4 = *(const LAS f32x4*)(Wv + 4096), kd4 = *(const LAS f32x4*)(Wv + 6144), r4 = *(const LAS f32x4*)(Wv + 8192); float vv = Vv[0];
;       f32x4 xw4 = *(const LAS f32x4*)(Wv + 64), xkk4 = *(const LAS f32x4*)(Wv + 2048 + 64), xb4 = *(const LAS f32x4*)(Wv + 4096 + 64), xkd4 = *(const LAS f32x4*)(Wv + 6144 + 64), xr4 = *(const LAS f32x4*)(Wv + 8192 + 64); float xvv = Vv[16];
; #pragma unroll 16
;       for (int t = 0; t < 32; ++t) {
;         const int tn = t + 2;
;         const f32x4 nw4 = *(const LAS f32x4*)(Wv + tn * 64), nkk4 = *(const LAS f32x4*)(Wv + 2048 + tn * 64), nb4 = *(const LAS f32x4*)(Wv + 4096 + tn * 64), nkd4 = *(const LAS f32x4*)(Wv + 6144 + tn * 64), nr4 = *(const LAS f32x4*)(Wv + 8192 + tn * 64);
;         const float nvv = Vv[tn * 16];
;         const f32x4 pa = S * kk4;
;         const f32x4 t1 = S * w4 + vv * kd4;
;         float sa = (pa[0] + pa[2]) + (pa[1] + pa[3]);
;         sa = row16_sum(sa);
;         S = t1 + sa * b4;
;         const f32x4 py = S * r4;
;         ypw[t * 256] = (py[0] + py[2]) + (py[1] + py[3]);
;         w4 = xw4; kk4 = xkk4; b4 = xb4; kd4 = xkd4; r4 = xr4; vv = xvv;
;         xw4 = nw4; xkk4 = nkk4; xb4 = nb4; xkd4 = nkd4; xr4 = nr4; xvv = nvv;
;       }
;       __syncthreads();
	v_add_f32_e32 v0, v6, v7
	v_pk_mul_f32 v[6:7], v[78:79], v[4:5]
	v_pk_fma_f32 v[6:7], v[76:77], v[2:3], v[6:7]
	v_add_f32_dpp v0, v0, v0 quad_perm:[1,0,3,2] row_mask:0xf bank_mask:0xf bound_ctrl:1
	v_pk_mul_f32 v[10:11], v[26:27], v[14:15] op_sel:[0,1] op_sel_hi:[1,1]
	v_pk_mul_f32 v[8:9], v[24:25], v[14:15] op_sel:[0,1] op_sel_hi:[1,1]
	v_add_f32_dpp v0, v0, v0 quad_perm:[2,3,0,1] row_mask:0xf bank_mask:0xf bound_ctrl:1
	ds_read_b128 v[64:67], v83 offset:32000
	ds_read_b128 v[68:71], v83 offset:7424
	ds_read_b128 v[72:75], v83 offset:23808
	ds_read_b128 v[76:79], v83 offset:40192
	ds_read_b128 v[20:23], v83 offset:15872
	v_add_f32_e32 v86, v6, v7
	v_add_f32_dpp v0, v0, v0 row_half_mirror row_mask:0xf bank_mask:0xf bound_ctrl:1
	v_pk_fma_f32 v[10:11], v[30:31], v[4:5], v[10:11]
	v_pk_fma_f32 v[8:9], v[28:29], v[2:3], v[8:9]
	v_add_f32_dpp v0, v0, v0 row_mirror row_mask:0xf bank_mask:0xf bound_ctrl:1
	v_pk_fma_f32 v[4:5], v[34:35], v[0:1], v[10:11] op_sel_hi:[1,0,1]
	v_pk_mul_f32 v[6:7], v[42:43], v[4:5]
	v_pk_fma_f32 v[2:3], v[32:33], v[0:1], v[8:9] op_sel_hi:[1,0,1]
	v_pk_fma_f32 v[6:7], v[40:41], v[2:3], v[6:7]
	s_waitcnt lgkmcnt(6)
	v_add_f32_e32 v0, v6, v7
	v_pk_mul_f32 v[6:7], v[38:39], v[4:5]
	v_pk_fma_f32 v[6:7], v[36:37], v[2:3], v[6:7]
	v_add_f32_dpp v0, v0, v0 quad_perm:[1,0,3,2] row_mask:0xf bank_mask:0xf bound_ctrl:1
	v_pk_mul_f32 v[10:11], v[46:47], v[16:17] op_sel_hi:[1,0]
	v_pk_mul_f32 v[8:9], v[44:45], v[16:17] op_sel_hi:[1,0]
	v_add_f32_dpp v0, v0, v0 quad_perm:[2,3,0,1] row_mask:0xf bank_mask:0xf bound_ctrl:1
	ds_read_b128 v[24:27], v83 offset:32256
	ds_read_b128 v[28:31], v83 offset:7680
	ds_read_b128 v[32:35], v83 offset:24064
	ds_read_b128 v[36:39], v83 offset:40448
	ds_read_b128 v[40:43], v83 offset:16128
	v_add_f32_e32 v87, v6, v7
	ds_write2st64_b32 v85, v86, v87 offset0:104 offset1:108
	v_add_f32_dpp v0, v0, v0 row_half_mirror row_mask:0xf bank_mask:0xf bound_ctrl:1
	v_pk_fma_f32 v[10:11], v[50:51], v[4:5], v[10:11]
	v_pk_fma_f32 v[8:9], v[48:49], v[2:3], v[8:9]
	v_add_f32_dpp v0, v0, v0 row_mirror row_mask:0xf bank_mask:0xf bound_ctrl:1
	v_pk_fma_f32 v[4:5], v[54:55], v[0:1], v[10:11] op_sel_hi:[1,0,1]
	v_pk_mul_f32 v[6:7], v[62:63], v[4:5]
	v_pk_fma_f32 v[2:3], v[52:53], v[0:1], v[8:9] op_sel_hi:[1,0,1]
	v_pk_fma_f32 v[6:7], v[60:61], v[2:3], v[6:7]
	s_waitcnt lgkmcnt(6)
	v_add_f32_e32 v0, v6, v7
	v_pk_mul_f32 v[6:7], v[58:59], v[4:5]
	v_pk_fma_f32 v[6:7], v[56:57], v[2:3], v[6:7]
	v_add_f32_dpp v0, v0, v0 quad_perm:[1,0,3,2] row_mask:0xf bank_mask:0xf bound_ctrl:1
	v_pk_mul_f32 v[10:11], v[66:67], v[16:17] op_sel:[0,1] op_sel_hi:[1,1]
	v_pk_mul_f32 v[8:9], v[64:65], v[16:17] op_sel:[0,1] op_sel_hi:[1,1]
	v_add_f32_dpp v0, v0, v0 quad_perm:[2,3,0,1] row_mask:0xf bank_mask:0xf bound_ctrl:1
	ds_read_b128 v[44:47], v83 offset:32512
	ds_read_b128 v[48:51], v83 offset:7936
	ds_read_b128 v[52:55], v83 offset:24320
	ds_read_b128 v[56:59], v83 offset:40704
	v_add_f32_e32 v86, v6, v7
	v_add_f32_dpp v0, v0, v0 row_half_mirror row_mask:0xf bank_mask:0xf bound_ctrl:1
	v_pk_fma_f32 v[10:11], v[70:71], v[4:5], v[10:11]
	v_pk_fma_f32 v[8:9], v[68:69], v[2:3], v[8:9]
	v_add_f32_dpp v0, v0, v0 row_mirror row_mask:0xf bank_mask:0xf bound_ctrl:1
	v_pk_fma_f32 v[4:5], v[74:75], v[0:1], v[10:11] op_sel_hi:[1,0,1]
	v_pk_mul_f32 v[6:7], v[22:23], v[4:5]
	v_pk_fma_f32 v[2:3], v[72:73], v[0:1], v[8:9] op_sel_hi:[1,0,1]
	v_pk_fma_f32 v[6:7], v[20:21], v[2:3], v[6:7]
	s_waitcnt lgkmcnt(5)
	v_add_f32_e32 v0, v6, v7
	v_pk_mul_f32 v[6:7], v[78:79], v[4:5]
	v_pk_fma_f32 v[6:7], v[76:77], v[2:3], v[6:7]
	v_add_f32_dpp v0, v0, v0 quad_perm:[1,0,3,2] row_mask:0xf bank_mask:0xf bound_ctrl:1
	v_pk_mul_f32 v[10:11], v[26:27], v[18:19] op_sel_hi:[1,0]
	v_pk_mul_f32 v[8:9], v[24:25], v[18:19] op_sel_hi:[1,0]
	v_add_f32_dpp v0, v0, v0 quad_perm:[2,3,0,1] row_mask:0xf bank_mask:0xf bound_ctrl:1
	v_add_f32_e32 v87, v6, v7
	ds_write2st64_b32 v85, v86, v87 offset0:112 offset1:116
	v_add_f32_dpp v0, v0, v0 row_half_mirror row_mask:0xf bank_mask:0xf bound_ctrl:1
	v_pk_fma_f32 v[10:11], v[30:31], v[4:5], v[10:11]
	v_pk_fma_f32 v[8:9], v[28:29], v[2:3], v[8:9]
	v_add_f32_dpp v0, v0, v0 row_mirror row_mask:0xf bank_mask:0xf bound_ctrl:1
	v_pk_fma_f32 v[4:5], v[34:35], v[0:1], v[10:11] op_sel_hi:[1,0,1]
	v_pk_mul_f32 v[6:7], v[42:43], v[4:5]
	v_pk_fma_f32 v[2:3], v[32:33], v[0:1], v[8:9] op_sel_hi:[1,0,1]
	v_pk_fma_f32 v[6:7], v[40:41], v[2:3], v[6:7]
	s_waitcnt lgkmcnt(1)
	v_add_f32_e32 v0, v6, v7
	v_pk_mul_f32 v[6:7], v[38:39], v[4:5]
	v_pk_fma_f32 v[6:7], v[36:37], v[2:3], v[6:7]
	v_add_f32_dpp v0, v0, v0 quad_perm:[1,0,3,2] row_mask:0xf bank_mask:0xf bound_ctrl:1
	v_pk_mul_f32 v[10:11], v[46:47], v[18:19] op_sel:[0,1] op_sel_hi:[1,1]
	v_pk_mul_f32 v[8:9], v[44:45], v[18:19] op_sel:[0,1] op_sel_hi:[1,1]
	v_add_f32_dpp v0, v0, v0 quad_perm:[2,3,0,1] row_mask:0xf bank_mask:0xf bound_ctrl:1
	v_add_f32_e32 v86, v6, v7
	s_nop 0
	v_add_f32_dpp v0, v0, v0 row_half_mirror row_mask:0xf bank_mask:0xf bound_ctrl:1
	v_pk_fma_f32 v[10:11], v[50:51], v[4:5], v[10:11]
	v_pk_fma_f32 v[8:9], v[48:49], v[2:3], v[8:9]
	v_add_f32_dpp v0, v0, v0 row_mirror row_mask:0xf bank_mask:0xf bound_ctrl:1
	v_pk_fma_f32 v[4:5], v[54:55], v[0:1], v[10:11] op_sel_hi:[1,0,1]
	v_pk_fma_f32 v[2:3], v[52:53], v[0:1], v[8:9] op_sel_hi:[1,0,1]
	v_pk_mul_f32 v[6:7], v[58:59], v[4:5]
	v_pk_fma_f32 v[6:7], v[56:57], v[2:3], v[6:7]
	s_nop 0
	v_add_f32_e32 v87, v6, v7
	ds_write2st64_b32 v85, v86, v87 offset0:120 offset1:124
	s_add_i32 s8, s8, 2
	s_cmpk_eq_i32 s8, 0x88
	s_waitcnt lgkmcnt(0)
	s_barrier
	s_cbranch_scc0 .Lrwc_scan
